# k7 plus lead-half waves skip the pre-barrier LDS wait (kept after barrier); lag half unchanged
# baseline (speedup 1.0000x reference)
; #define PG8_STAGE(bufoff, gbase, voff) do { _Pragma("unroll") for (int _i = 0; _i < 2; ++_i) \
;         __builtin_amdgcn_global_load_lds((const unsigned*)((const char*)(gbase) + (voff)[_i]), (LAS unsigned*)(lds + (bufoff) + ldsw + _i * 8192), 16, 0, 0); } while (0)
; #define PG8_LDA(dst, b, h) do { _Pragma("unroll") for (int m = 0; m < 4; ++m) _Pragma("unroll") for (int k = 0; k < 2; ++k) dst[m][k] = *(const LAS bf16x8*)(lds + PG8_SA(b, h) + aoff + m * 2048 + k * 1024); } while (0)
; #define PG8_LDB(dst, b, h) do { _Pragma("unroll") for (int n = 0; n < 2; ++n) _Pragma("unroll") for (int k = 0; k < 2; ++k) dst[n][k] = *(const LAS bf16x8*)(lds + PG8_SB(b, h) + boff + n * 2048 + k * 1024); } while (0)
; #define PG8_MMA(ai, bj, At, Bt) do { __builtin_amdgcn_s_setprio(1); _Pragma("unroll") for (int m = 0; m < 4; ++m) _Pragma("unroll") for (int n = 0; n < 2; ++n) _Pragma("unroll") for (int k = 0; k < 2; ++k) \
;         acc[ai][bj][m][n] = __builtin_amdgcn_mfma_f32_16x16x32_bf16(Bt[n][k], At[m][k], acc[ai][bj][m][n], 0, 0, 0); __builtin_amdgcn_s_setprio(0); } while (0)
; #define PG8_WAIT_V(n) asm volatile("s_waitcnt vmcnt(" #n ")" ::: "memory")
; #define PG8_BAR __builtin_amdgcn_s_barrier()
; template <class Epi, class Sched, bool ALIGN_EPI = true>
; __device__ __forceinline__ void gemm_phase(LAS unsigned char* lds, const Gemm g, const Sched& S, const Epi& E) {
;     ...
;             PG8_LDB(B0, 0, 0); PG8_LDB(B1, 0, 1); PG8_SCHED; PG8_LDA(At, 0, 0); PG8_STAGE(PG8_SA(1, 1), a1 + hA, voffA);
;             PG8_WAIT_V(8); PG8_WAIT_L(0); PG8_BAR; PG8_MMA(0, 0, At, B0); PG8_MMA(0, 1, At, B1); PG8_BAR; PG8_SCHED;
;             PG8_LDA(At, 0, 1); PG8_STAGE(PG8_SB(0, 0), b2, voffB); PG8_STAGE(PG8_SB(0, 1), b2 + hB, voffB); PG8_STAGE(PG8_SA(0, 0), a2, voffA);
;             PG8_WAIT_V(8); PG8_WAIT_L(0); PG8_BAR; PG8_MMA(1, 0, At, B0); PG8_MMA(1, 1, At, B1); PG8_BAR; PG8_SCHED;
;             PG8_LDB(B0, 1, 0); PG8_LDB(B1, 1, 1); PG8_SCHED; PG8_LDA(At, 1, 0); PG8_STAGE(PG8_SA(0, 1), a2 + hA, voffA);
;             PG8_WAIT_V(8); PG8_WAIT_L(0); PG8_BAR; PG8_MMA(0, 0, At, B0); PG8_MMA(0, 1, At, B1); PG8_BAR; PG8_SCHED;
;             PG8_LDA(At, 1, 1); PG8_STAGE(PG8_SB(1, 0), b3, voffB); PG8_STAGE(PG8_SB(1, 1), b3 + hB, voffB); PG8_STAGE(PG8_SA(1, 0), a3, voffA);
;             PG8_WAIT_V(8); PG8_WAIT_L(0); PG8_BAR; PG8_MMA(1, 0, At, B0); PG8_MMA(1, 1, At, B1); PG8_BAR; PG8_SCHED;
.LBB0_77:
	s_add_u32 s26, s6, 0xfff80080
	s_addc_u32 s27, s7, -1
	s_add_i32 s30, 0, 0x10000
	s_cmp_eq_u32 s25, 28
	s_cselect_b32 s45, s15, s27
	s_cselect_b32 s44, s17, s26
	s_cselect_b32 s43, s13, s24
	s_cselect_b32 s42, s18, s19
	s_add_i32 s31, 0, 0x14000
	v_add_u32_e32 v144, s30, v166
	v_add_u32_e32 v156, s31, v166
	ds_read_b128 v[132:135], v144
	ds_read_b128 v[136:139], v144 offset:1024
	ds_read_b128 v[140:143], v144 offset:2048
	ds_read_b128 v[144:147], v144 offset:3072
	ds_read_b128 v[170:173], v156
	ds_read_b128 v[174:177], v156 offset:1024
	ds_read_b128 v[178:181], v156 offset:2048
	ds_read_b128 v[182:185], v156 offset:3072
	v_lshl_add_u64 v[156:157], s[6:7], 0, v[152:153]
	s_add_i32 m0, s60, 0xc000
	ds_read_b128 v[186:189], v168
	ds_read_b128 v[190:193], v168 offset:1024
	ds_read_b128 v[194:197], v168 offset:2048
	ds_read_b128 v[204:207], v168 offset:3072
	ds_read_b128 v[208:211], v168 offset:4096
	ds_read_b128 v[212:215], v168 offset:5120
	ds_read_b128 v[216:219], v168 offset:6144
	ds_read_b128 v[220:223], v168 offset:7168
	global_load_lds_dwordx4 v[156:157], off
	v_lshl_add_u64 v[156:157], s[6:7], 0, v[154:155]
	s_add_i32 m0, s60, 0xe000
	s_nop 0
	global_load_lds_dwordx4 v[156:157], off
	s_waitcnt vmcnt(8)
	s_cmp_lg_u64 s[10:11], 0
	s_cbranch_scc1 .Llgk_77_0
	s_waitcnt lgkmcnt(0)
.Llgk_77_0:
	s_barrier
	s_setprio 1
	s_waitcnt lgkmcnt(0)
	v_mfma_f32_16x16x32_bf16 v[128:131], v[132:135], v[186:189], v[128:131]
	v_mfma_f32_16x16x32_bf16 v[124:127], v[140:143], v[186:189], v[124:127]
	v_mfma_f32_16x16x32_bf16 v[116:119], v[132:135], v[194:197], v[116:119]
	v_mfma_f32_16x16x32_bf16 v[112:115], v[140:143], v[194:197], v[112:115]
	v_mfma_f32_16x16x32_bf16 v[104:107], v[132:135], v[208:211], v[104:107]
	v_mfma_f32_16x16x32_bf16 v[96:99], v[140:143], v[208:211], v[96:99]
	v_mfma_f32_16x16x32_bf16 v[88:91], v[132:135], v[216:219], v[88:91]
	v_mfma_f32_16x16x32_bf16 v[80:83], v[140:143], v[216:219], v[80:83]
	v_mfma_f32_16x16x32_bf16 v[128:131], v[136:139], v[190:193], v[128:131]
	v_mfma_f32_16x16x32_bf16 v[124:127], v[144:147], v[190:193], v[124:127]
	v_mfma_f32_16x16x32_bf16 v[116:119], v[136:139], v[204:207], v[116:119]
	v_mfma_f32_16x16x32_bf16 v[112:115], v[144:147], v[204:207], v[112:115]
	v_mfma_f32_16x16x32_bf16 v[104:107], v[136:139], v[212:215], v[104:107]
	v_mfma_f32_16x16x32_bf16 v[96:99], v[144:147], v[212:215], v[96:99]
	v_mfma_f32_16x16x32_bf16 v[88:91], v[136:139], v[220:223], v[88:91]
	v_mfma_f32_16x16x32_bf16 v[80:83], v[144:147], v[220:223], v[80:83]
	s_setprio 0
	s_setprio 1
	v_mfma_f32_16x16x32_bf16 v[120:123], v[170:173], v[186:189], v[120:123]
	v_mfma_f32_16x16x32_bf16 v[108:111], v[178:181], v[186:189], v[108:111]
	v_mfma_f32_16x16x32_bf16 v[100:103], v[170:173], v[194:197], v[100:103]
	v_mfma_f32_16x16x32_bf16 v[92:95], v[178:181], v[194:197], v[92:95]
	v_mfma_f32_16x16x32_bf16 v[84:87], v[170:173], v[208:211], v[84:87]
	v_mfma_f32_16x16x32_bf16 v[76:79], v[178:181], v[208:211], v[76:79]
	v_mfma_f32_16x16x32_bf16 v[72:75], v[170:173], v[216:219], v[72:75]
	v_mfma_f32_16x16x32_bf16 v[68:71], v[178:181], v[216:219], v[68:71]
	v_mfma_f32_16x16x32_bf16 v[120:123], v[174:177], v[190:193], v[120:123]
	v_mfma_f32_16x16x32_bf16 v[108:111], v[182:185], v[190:193], v[108:111]
	v_mfma_f32_16x16x32_bf16 v[100:103], v[174:177], v[204:207], v[100:103]
	v_mfma_f32_16x16x32_bf16 v[92:95], v[182:185], v[204:207], v[92:95]
	s_setprio 2
	s_barrier
	v_mfma_f32_16x16x32_bf16 v[84:87], v[174:177], v[212:215], v[84:87]
	v_mfma_f32_16x16x32_bf16 v[76:79], v[182:185], v[212:215], v[76:79]
	v_mfma_f32_16x16x32_bf16 v[72:75], v[174:177], v[220:223], v[72:75]
	v_mfma_f32_16x16x32_bf16 v[68:71], v[182:185], v[220:223], v[68:71]
	s_setprio 0
	s_add_i32 s26, s30, s59
	v_lshl_add_u64 v[156:157], s[42:43], 0, v[2:3]
	s_mov_b32 m0, s26
	ds_read_b128 v[186:189], v168 offset:16384
	ds_read_b128 v[190:193], v168 offset:17408
	ds_read_b128 v[194:197], v168 offset:18432
	ds_read_b128 v[204:207], v168 offset:19456
	ds_read_b128 v[208:211], v168 offset:20480
	ds_read_b128 v[212:215], v168 offset:21504
	ds_read_b128 v[216:219], v168 offset:22528
	ds_read_b128 v[220:223], v168 offset:23552
	global_load_lds_dwordx4 v[156:157], off
	s_add_i32 m0, s26, 0x2000
	s_add_u32 s26, s42, 0x80000
	v_lshl_add_u64 v[164:165], s[42:43], 0, v[0:1]
	s_addc_u32 s27, s43, 0
	s_add_i32 s30, s31, s59
	global_load_lds_dwordx4 v[164:165], off
	v_lshl_add_u64 v[224:225], s[26:27], 0, v[2:3]
	s_mov_b32 m0, s30
	v_lshl_add_u64 v[226:227], s[44:45], 0, v[148:149]
	global_load_lds_dwordx4 v[224:225], off
	v_lshl_add_u64 v[224:225], s[26:27], 0, v[0:1]
	s_add_i32 m0, s30, 0x2000
	s_nop 0
	global_load_lds_dwordx4 v[224:225], off
	v_lshl_add_u64 v[224:225], s[44:45], 0, v[150:151]
	s_mov_b32 m0, s60
	s_nop 0
	global_load_lds_dwordx4 v[224:225], off
	s_mov_b32 m0, s61
	s_nop 0
	global_load_lds_dwordx4 v[226:227], off
	s_waitcnt vmcnt(8)
	s_cmp_lg_u64 s[10:11], 0
	s_cbranch_scc1 .Llgk_77_1
	s_waitcnt lgkmcnt(0)
; #define PG8_STAGE(bufoff, gbase, voff) do { _Pragma("unroll") for (int _i = 0; _i < 2; ++_i) \
;         __builtin_amdgcn_global_load_lds((const unsigned*)((const char*)(gbase) + (voff)[_i]), (LAS unsigned*)(lds + (bufoff) + ldsw + _i * 8192), 16, 0, 0); } while (0)
; #define PG8_LDA(dst, b, h) do { _Pragma("unroll") for (int m = 0; m < 4; ++m) _Pragma("unroll") for (int k = 0; k < 2; ++k) dst[m][k] = *(const LAS bf16x8*)(lds + PG8_SA(b, h) + aoff + m * 2048 + k * 1024); } while (0)
; #define PG8_LDB(dst, b, h) do { _Pragma("unroll") for (int n = 0; n < 2; ++n) _Pragma("unroll") for (int k = 0; k < 2; ++k) dst[n][k] = *(const LAS bf16x8*)(lds + PG8_SB(b, h) + boff + n * 2048 + k * 1024); } while (0)
; #define PG8_MMA(ai, bj, At, Bt) do { __builtin_amdgcn_s_setprio(1); _Pragma("unroll") for (int m = 0; m < 4; ++m) _Pragma("unroll") for (int n = 0; n < 2; ++n) _Pragma("unroll") for (int k = 0; k < 2; ++k) \
;         acc[ai][bj][m][n] = __builtin_amdgcn_mfma_f32_16x16x32_bf16(Bt[n][k], At[m][k], acc[ai][bj][m][n], 0, 0, 0); __builtin_amdgcn_s_setprio(0); } while (0)
; #define PG8_WAIT_V(n) asm volatile("s_waitcnt vmcnt(" #n ")" ::: "memory")
; #define PG8_WAIT_L(n) asm volatile("s_waitcnt lgkmcnt(" #n ")" ::: "memory")
; #define PG8_BAR __builtin_amdgcn_s_barrier()
; #define PG8_SCHED __builtin_amdgcn_sched_barrier(0)
; template <class Epi, class Sched, bool ALIGN_EPI = true>
; __device__ __forceinline__ void gemm_phase(LAS unsigned char* lds, const Gemm g, const Sched& S, const Epi& E) {
;     ...
;             PG8_WAIT_V(8); PG8_WAIT_L(0); PG8_BAR; PG8_MMA(1, 0, At, B0); PG8_MMA(1, 1, At, B1); PG8_BAR; PG8_SCHED;
;             PG8_LDB(B0, 1, 0); PG8_LDB(B1, 1, 1); PG8_SCHED; PG8_LDA(At, 1, 0); PG8_STAGE(PG8_SA(0, 1), a2 + hA, voffA);
;             PG8_WAIT_V(8); PG8_WAIT_L(0); PG8_BAR; PG8_MMA(0, 0, At, B0); PG8_MMA(0, 1, At, B1); PG8_BAR; PG8_SCHED;
.Llgk_77_1:
	s_barrier
	s_setprio 1
	s_waitcnt lgkmcnt(0)
	v_mfma_f32_16x16x32_bf16 v[64:67], v[132:135], v[186:189], v[64:67]
	v_mfma_f32_16x16x32_bf16 v[60:63], v[140:143], v[186:189], v[60:63]
	v_mfma_f32_16x16x32_bf16 v[56:59], v[132:135], v[194:197], v[56:59]
	v_mfma_f32_16x16x32_bf16 v[48:51], v[140:143], v[194:197], v[48:51]
	v_mfma_f32_16x16x32_bf16 v[40:43], v[132:135], v[208:211], v[40:43]
	v_mfma_f32_16x16x32_bf16 v[32:35], v[140:143], v[208:211], v[32:35]
	v_mfma_f32_16x16x32_bf16 v[24:27], v[132:135], v[216:219], v[24:27]
	v_mfma_f32_16x16x32_bf16 v[16:19], v[140:143], v[216:219], v[16:19]
	v_mfma_f32_16x16x32_bf16 v[64:67], v[136:139], v[190:193], v[64:67]
	v_mfma_f32_16x16x32_bf16 v[60:63], v[144:147], v[190:193], v[60:63]
	v_mfma_f32_16x16x32_bf16 v[56:59], v[136:139], v[204:207], v[56:59]
	v_mfma_f32_16x16x32_bf16 v[48:51], v[144:147], v[204:207], v[48:51]
	v_mfma_f32_16x16x32_bf16 v[40:43], v[136:139], v[212:215], v[40:43]
	v_mfma_f32_16x16x32_bf16 v[32:35], v[144:147], v[212:215], v[32:35]
	v_mfma_f32_16x16x32_bf16 v[24:27], v[136:139], v[220:223], v[24:27]
	v_mfma_f32_16x16x32_bf16 v[16:19], v[144:147], v[220:223], v[16:19]
	s_setprio 0
	s_setprio 1
	v_mfma_f32_16x16x32_bf16 v[52:55], v[170:173], v[186:189], v[52:55]
	v_mfma_f32_16x16x32_bf16 v[44:47], v[178:181], v[186:189], v[44:47]
	v_mfma_f32_16x16x32_bf16 v[36:39], v[170:173], v[194:197], v[36:39]
	v_mfma_f32_16x16x32_bf16 v[28:31], v[178:181], v[194:197], v[28:31]
	v_mfma_f32_16x16x32_bf16 v[20:23], v[170:173], v[208:211], v[20:23]
	v_mfma_f32_16x16x32_bf16 v[12:15], v[178:181], v[208:211], v[12:15]
	v_mfma_f32_16x16x32_bf16 v[8:11], v[170:173], v[216:219], v[8:11]
	v_mfma_f32_16x16x32_bf16 v[4:7], v[178:181], v[216:219], v[4:7]
	v_mfma_f32_16x16x32_bf16 v[52:55], v[174:177], v[190:193], v[52:55]
	v_mfma_f32_16x16x32_bf16 v[44:47], v[182:185], v[190:193], v[44:47]
	v_mfma_f32_16x16x32_bf16 v[36:39], v[174:177], v[204:207], v[36:39]
	v_mfma_f32_16x16x32_bf16 v[28:31], v[182:185], v[204:207], v[28:31]
	s_setprio 2
	s_barrier
	v_mfma_f32_16x16x32_bf16 v[20:23], v[174:177], v[212:215], v[20:23]
	v_mfma_f32_16x16x32_bf16 v[12:15], v[182:185], v[212:215], v[12:15]
	v_mfma_f32_16x16x32_bf16 v[8:11], v[174:177], v[220:223], v[8:11]
	v_mfma_f32_16x16x32_bf16 v[4:7], v[182:185], v[220:223], v[4:7]
	s_setprio 0
	s_add_i32 s30, 0, 0x18000
	s_add_i32 s31, 0, 0x1c000
	v_add_u32_e32 v144, s30, v166
	v_add_u32_e32 v160, s31, v166
	ds_read_b128 v[132:135], v144
	ds_read_b128 v[136:139], v144 offset:1024
	ds_read_b128 v[140:143], v144 offset:2048
	ds_read_b128 v[144:147], v144 offset:3072
	ds_read_b128 v[170:173], v160
	ds_read_b128 v[174:177], v160 offset:1024
	ds_read_b128 v[178:181], v160 offset:2048
	ds_read_b128 v[182:185], v160 offset:3072
	s_add_u32 s26, s44, 0x80000
	s_addc_u32 s27, s45, 0
	s_mov_b32 m0, s62
	v_lshl_add_u64 v[228:229], s[26:27], 0, v[150:151]
	ds_read_b128 v[186:189], v168 offset:32768
	ds_read_b128 v[190:193], v168 offset:33792
	ds_read_b128 v[194:197], v168 offset:34816
	ds_read_b128 v[204:207], v168 offset:35840
	ds_read_b128 v[208:211], v168 offset:36864
	ds_read_b128 v[212:215], v168 offset:37888
	ds_read_b128 v[216:219], v168 offset:38912
	ds_read_b128 v[220:223], v168 offset:39936
	global_load_lds_dwordx4 v[228:229], off
	v_lshl_add_u64 v[228:229], s[26:27], 0, v[148:149]
	s_mov_b32 m0, s63
	s_nop 0
	global_load_lds_dwordx4 v[228:229], off
	s_waitcnt vmcnt(8)
	s_cmp_lg_u64 s[10:11], 0
	s_cbranch_scc1 .Llgk_77_2
	s_waitcnt lgkmcnt(0)
; #define PG8_STAGE(bufoff, gbase, voff) do { _Pragma("unroll") for (int _i = 0; _i < 2; ++_i) \
;         __builtin_amdgcn_global_load_lds((const unsigned*)((const char*)(gbase) + (voff)[_i]), (LAS unsigned*)(lds + (bufoff) + ldsw + _i * 8192), 16, 0, 0); } while (0)
; #define PG8_LDA(dst, b, h) do { _Pragma("unroll") for (int m = 0; m < 4; ++m) _Pragma("unroll") for (int k = 0; k < 2; ++k) dst[m][k] = *(const LAS bf16x8*)(lds + PG8_SA(b, h) + aoff + m * 2048 + k * 1024); } while (0)
; #define PG8_MMA(ai, bj, At, Bt) do { __builtin_amdgcn_s_setprio(1); _Pragma("unroll") for (int m = 0; m < 4; ++m) _Pragma("unroll") for (int n = 0; n < 2; ++n) _Pragma("unroll") for (int k = 0; k < 2; ++k) \
;         acc[ai][bj][m][n] = __builtin_amdgcn_mfma_f32_16x16x32_bf16(Bt[n][k], At[m][k], acc[ai][bj][m][n], 0, 0, 0); __builtin_amdgcn_s_setprio(0); } while (0)
; #define PG8_WAIT_V(n) asm volatile("s_waitcnt vmcnt(" #n ")" ::: "memory")
; #define PG8_WAIT_L(n) asm volatile("s_waitcnt lgkmcnt(" #n ")" ::: "memory")
; #define PG8_BAR __builtin_amdgcn_s_barrier()
; #define PG8_SCHED __builtin_amdgcn_sched_barrier(0)
; template <class Epi, class Sched, bool ALIGN_EPI = true>
; __device__ __forceinline__ void gemm_phase(LAS unsigned char* lds, const Gemm g, const Sched& S, const Epi& E) {
;     ...
;             PG8_WAIT_V(8); PG8_WAIT_L(0); PG8_BAR; PG8_MMA(0, 0, At, B0); PG8_MMA(0, 1, At, B1); PG8_BAR; PG8_SCHED;
;             PG8_LDA(At, 1, 1); PG8_STAGE(PG8_SB(1, 0), b3, voffB); PG8_STAGE(PG8_SB(1, 1), b3 + hB, voffB); PG8_STAGE(PG8_SA(1, 0), a3, voffA);
;             PG8_WAIT_V(8); PG8_WAIT_L(0); PG8_BAR; PG8_MMA(1, 0, At, B0); PG8_MMA(1, 1, At, B1); PG8_BAR; PG8_SCHED;
;         }
;         if constexpr (ALIGN_EPI) { if (wr == 0) PG8_BAR; }
.Llgk_77_2:
	s_barrier
	s_setprio 1
	s_waitcnt lgkmcnt(0)
	v_mfma_f32_16x16x32_bf16 v[128:131], v[132:135], v[186:189], v[128:131]
	v_mfma_f32_16x16x32_bf16 v[124:127], v[140:143], v[186:189], v[124:127]
	v_mfma_f32_16x16x32_bf16 v[116:119], v[132:135], v[194:197], v[116:119]
	v_mfma_f32_16x16x32_bf16 v[112:115], v[140:143], v[194:197], v[112:115]
	v_mfma_f32_16x16x32_bf16 v[104:107], v[132:135], v[208:211], v[104:107]
	v_mfma_f32_16x16x32_bf16 v[96:99], v[140:143], v[208:211], v[96:99]
	v_mfma_f32_16x16x32_bf16 v[88:91], v[132:135], v[216:219], v[88:91]
	v_mfma_f32_16x16x32_bf16 v[80:83], v[140:143], v[216:219], v[80:83]
	v_mfma_f32_16x16x32_bf16 v[128:131], v[136:139], v[190:193], v[128:131]
	v_mfma_f32_16x16x32_bf16 v[124:127], v[144:147], v[190:193], v[124:127]
	v_mfma_f32_16x16x32_bf16 v[116:119], v[136:139], v[204:207], v[116:119]
	v_mfma_f32_16x16x32_bf16 v[112:115], v[144:147], v[204:207], v[112:115]
	v_mfma_f32_16x16x32_bf16 v[104:107], v[136:139], v[212:215], v[104:107]
	v_mfma_f32_16x16x32_bf16 v[96:99], v[144:147], v[212:215], v[96:99]
	v_mfma_f32_16x16x32_bf16 v[88:91], v[136:139], v[220:223], v[88:91]
	v_mfma_f32_16x16x32_bf16 v[80:83], v[144:147], v[220:223], v[80:83]
	s_setprio 0
	s_setprio 1
	v_mfma_f32_16x16x32_bf16 v[120:123], v[170:173], v[186:189], v[120:123]
	v_mfma_f32_16x16x32_bf16 v[108:111], v[178:181], v[186:189], v[108:111]
	v_mfma_f32_16x16x32_bf16 v[100:103], v[170:173], v[194:197], v[100:103]
	v_mfma_f32_16x16x32_bf16 v[92:95], v[178:181], v[194:197], v[92:95]
	v_mfma_f32_16x16x32_bf16 v[84:87], v[170:173], v[208:211], v[84:87]
	v_mfma_f32_16x16x32_bf16 v[76:79], v[178:181], v[208:211], v[76:79]
	v_mfma_f32_16x16x32_bf16 v[72:75], v[170:173], v[216:219], v[72:75]
	v_mfma_f32_16x16x32_bf16 v[68:71], v[178:181], v[216:219], v[68:71]
	v_mfma_f32_16x16x32_bf16 v[120:123], v[174:177], v[190:193], v[120:123]
	v_mfma_f32_16x16x32_bf16 v[108:111], v[182:185], v[190:193], v[108:111]
	v_mfma_f32_16x16x32_bf16 v[100:103], v[174:177], v[204:207], v[100:103]
	v_mfma_f32_16x16x32_bf16 v[92:95], v[182:185], v[204:207], v[92:95]
	s_setprio 2
	s_barrier
	v_mfma_f32_16x16x32_bf16 v[84:87], v[174:177], v[212:215], v[84:87]
	v_mfma_f32_16x16x32_bf16 v[76:79], v[182:185], v[212:215], v[76:79]
	v_mfma_f32_16x16x32_bf16 v[72:75], v[174:177], v[220:223], v[72:75]
	v_mfma_f32_16x16x32_bf16 v[68:71], v[182:185], v[220:223], v[68:71]
	s_setprio 0
	s_add_i32 s26, s30, s59
	v_lshl_add_u64 v[156:157], v[156:157], 0, s[86:87]
	s_mov_b32 m0, s26
	ds_read_b128 v[186:189], v168 offset:49152
	ds_read_b128 v[190:193], v168 offset:50176
	ds_read_b128 v[194:197], v168 offset:51200
	ds_read_b128 v[204:207], v168 offset:52224
	ds_read_b128 v[208:211], v168 offset:53248
	ds_read_b128 v[212:215], v168 offset:54272
	ds_read_b128 v[216:219], v168 offset:55296
	ds_read_b128 v[220:223], v168 offset:56320
	global_load_lds_dwordx4 v[156:157], off
	s_add_i32 m0, s26, 0x2000
	s_add_u32 s26, s42, 0x80080
	v_lshl_add_u64 v[156:157], v[164:165], 0, s[86:87]
	s_addc_u32 s27, s43, 0
	s_add_i32 s30, s31, s59
	global_load_lds_dwordx4 v[156:157], off
	v_lshl_add_u64 v[156:157], s[26:27], 0, v[2:3]
	s_mov_b32 m0, s30
	s_nop 0
	global_load_lds_dwordx4 v[156:157], off
	v_lshl_add_u64 v[156:157], s[26:27], 0, v[0:1]
	s_add_i32 m0, s30, 0x2000
	s_nop 0
	global_load_lds_dwordx4 v[156:157], off
	v_lshl_add_u64 v[156:157], v[224:225], 0, s[86:87]
	s_mov_b32 m0, s64
	s_nop 0
	global_load_lds_dwordx4 v[156:157], off
	v_lshl_add_u64 v[156:157], v[226:227], 0, s[86:87]
	s_mov_b32 m0, s65
	s_nop 0
	global_load_lds_dwordx4 v[156:157], off
	s_waitcnt vmcnt(8)
	s_cmp_lg_u64 s[10:11], 0
	s_cbranch_scc1 .Llgk_77_3
	s_waitcnt lgkmcnt(0)
.Llgk_77_3:
	s_barrier
	s_setprio 1
	s_waitcnt lgkmcnt(0)
	v_mfma_f32_16x16x32_bf16 v[64:67], v[132:135], v[186:189], v[64:67]
	v_mfma_f32_16x16x32_bf16 v[60:63], v[140:143], v[186:189], v[60:63]
	v_mfma_f32_16x16x32_bf16 v[56:59], v[132:135], v[194:197], v[56:59]
	v_mfma_f32_16x16x32_bf16 v[48:51], v[140:143], v[194:197], v[48:51]
	v_mfma_f32_16x16x32_bf16 v[40:43], v[132:135], v[208:211], v[40:43]
	v_mfma_f32_16x16x32_bf16 v[32:35], v[140:143], v[208:211], v[32:35]
	v_mfma_f32_16x16x32_bf16 v[24:27], v[132:135], v[216:219], v[24:27]
	v_mfma_f32_16x16x32_bf16 v[16:19], v[140:143], v[216:219], v[16:19]
	v_mfma_f32_16x16x32_bf16 v[64:67], v[136:139], v[190:193], v[64:67]
	v_mfma_f32_16x16x32_bf16 v[60:63], v[144:147], v[190:193], v[60:63]
	v_mfma_f32_16x16x32_bf16 v[56:59], v[136:139], v[204:207], v[56:59]
	v_mfma_f32_16x16x32_bf16 v[48:51], v[144:147], v[204:207], v[48:51]
	v_mfma_f32_16x16x32_bf16 v[40:43], v[136:139], v[212:215], v[40:43]
	v_mfma_f32_16x16x32_bf16 v[32:35], v[144:147], v[212:215], v[32:35]
	v_mfma_f32_16x16x32_bf16 v[24:27], v[136:139], v[220:223], v[24:27]
	v_mfma_f32_16x16x32_bf16 v[16:19], v[144:147], v[220:223], v[16:19]
	s_setprio 0
	s_setprio 1
	v_mfma_f32_16x16x32_bf16 v[52:55], v[170:173], v[186:189], v[52:55]
	v_mfma_f32_16x16x32_bf16 v[44:47], v[178:181], v[186:189], v[44:47]
	v_mfma_f32_16x16x32_bf16 v[36:39], v[170:173], v[194:197], v[36:39]
	v_mfma_f32_16x16x32_bf16 v[28:31], v[178:181], v[194:197], v[28:31]
	v_mfma_f32_16x16x32_bf16 v[20:23], v[170:173], v[208:211], v[20:23]
	v_mfma_f32_16x16x32_bf16 v[12:15], v[178:181], v[208:211], v[12:15]
	v_mfma_f32_16x16x32_bf16 v[8:11], v[170:173], v[216:219], v[8:11]
	v_mfma_f32_16x16x32_bf16 v[4:7], v[178:181], v[216:219], v[4:7]
	v_mfma_f32_16x16x32_bf16 v[52:55], v[174:177], v[190:193], v[52:55]
	v_mfma_f32_16x16x32_bf16 v[44:47], v[182:185], v[190:193], v[44:47]
	v_mfma_f32_16x16x32_bf16 v[36:39], v[174:177], v[204:207], v[36:39]
	v_mfma_f32_16x16x32_bf16 v[28:31], v[182:185], v[204:207], v[28:31]
	s_setprio 2
	s_barrier
	v_mfma_f32_16x16x32_bf16 v[20:23], v[174:177], v[212:215], v[20:23]
	v_mfma_f32_16x16x32_bf16 v[12:15], v[182:185], v[212:215], v[12:15]
	v_mfma_f32_16x16x32_bf16 v[8:11], v[174:177], v[220:223], v[8:11]
	v_mfma_f32_16x16x32_bf16 v[4:7], v[182:185], v[220:223], v[4:7]
	s_setprio 0
	s_add_i32 s25, s25, 2
	s_add_u32 s6, s6, 0x100
	s_addc_u32 s7, s7, 0
	s_add_u32 s19, s19, 0x100
	s_addc_u32 s24, s24, 0
	s_cmp_gt_u32 s25, 29
	s_cbranch_scc0 .LBB0_77
	s_and_b64 vcc, exec, s[10:11]
	s_cbranch_vccz .LBB0_80
	s_barrier

; #define PG8_STAGE(bufoff, gbase, voff) do { _Pragma("unroll") for (int _i = 0; _i < 2; ++_i) \
;         __builtin_amdgcn_global_load_lds((const unsigned*)((const char*)(gbase) + (voff)[_i]), (LAS unsigned*)(lds + (bufoff) + ldsw + _i * 8192), 16, 0, 0); } while (0)
; #define PG8_LDA(dst, b, h) do { _Pragma("unroll") for (int m = 0; m < 4; ++m) _Pragma("unroll") for (int k = 0; k < 2; ++k) dst[m][k] = *(const LAS bf16x8*)(lds + PG8_SA(b, h) + aoff + m * 2048 + k * 1024); } while (0)
; #define PG8_LDB(dst, b, h) do { _Pragma("unroll") for (int n = 0; n < 2; ++n) _Pragma("unroll") for (int k = 0; k < 2; ++k) dst[n][k] = *(const LAS bf16x8*)(lds + PG8_SB(b, h) + boff + n * 2048 + k * 1024); } while (0)
; #define PG8_MMA(ai, bj, At, Bt) do { __builtin_amdgcn_s_setprio(1); _Pragma("unroll") for (int m = 0; m < 4; ++m) _Pragma("unroll") for (int n = 0; n < 2; ++n) _Pragma("unroll") for (int k = 0; k < 2; ++k) \
;         acc[ai][bj][m][n] = __builtin_amdgcn_mfma_f32_16x16x32_bf16(Bt[n][k], At[m][k], acc[ai][bj][m][n], 0, 0, 0); __builtin_amdgcn_s_setprio(0); } while (0)
; #define PG8_WAIT_V(n) asm volatile("s_waitcnt vmcnt(" #n ")" ::: "memory")
; #define PG8_WAIT_L(n) asm volatile("s_waitcnt lgkmcnt(" #n ")" ::: "memory")
; #define PG8_BAR __builtin_amdgcn_s_barrier()
; #define PG8_SCHED __builtin_amdgcn_sched_barrier(0)
; template <class Epi, class Sched, bool ALIGN_EPI = true>
; __device__ __forceinline__ void gemm_phase(LAS unsigned char* lds, const Gemm g, const Sched& S, const Epi& E) {
;     ...
;             PG8_LDB(B0, 0, 0); PG8_LDB(B1, 0, 1); PG8_SCHED; PG8_LDA(At, 0, 0); PG8_STAGE(PG8_SA(1, 1), a1 + hA, voffA);
;             PG8_WAIT_V(8); PG8_WAIT_L(0); PG8_BAR; PG8_MMA(0, 0, At, B0); PG8_MMA(0, 1, At, B1); PG8_BAR; PG8_SCHED;
;             PG8_LDA(At, 0, 1); PG8_STAGE(PG8_SB(0, 0), b2, voffB); PG8_STAGE(PG8_SB(0, 1), b2 + hB, voffB); PG8_STAGE(PG8_SA(0, 0), a2, voffA);
;             PG8_WAIT_V(8); PG8_WAIT_L(0); PG8_BAR; PG8_MMA(1, 0, At, B0); PG8_MMA(1, 1, At, B1); PG8_BAR; PG8_SCHED;
.LBB0_218:
	s_add_u32 s27, s38, 0xfff80080
	s_addc_u32 s30, s39, -1
	s_add_i32 s31, 0, 0x10000
	s_cmp_eq_u32 s26, 28
	s_cselect_b32 s43, s11, s30
	s_cselect_b32 s42, s18, s27
	v_add_u32_e32 v156, s31, v145
	s_cselect_b32 s41, s9, s25
	s_cselect_b32 s40, s19, s24
	s_add_i32 s27, 0, 0x14000
	ds_read_b128 v[140:143], v156
	ds_read_b128 v[148:151], v156 offset:1024
	ds_read_b128 v[152:155], v156 offset:2048
	ds_read_b128 v[164:167], v156 offset:3072
	v_add_u32_e32 v156, s27, v145
	ds_read_b128 v[168:171], v156
	ds_read_b128 v[172:175], v156 offset:1024
	ds_read_b128 v[176:179], v156 offset:2048
	ds_read_b128 v[180:183], v156 offset:3072
	v_lshl_add_u64 v[156:157], s[38:39], 0, v[136:137]
	s_add_i32 m0, s58, 0xc000
	ds_read_b128 v[184:187], v147
	ds_read_b128 v[188:191], v147 offset:1024
	ds_read_b128 v[192:195], v147 offset:2048
	ds_read_b128 v[204:207], v147 offset:3072
	ds_read_b128 v[208:211], v147 offset:4096
	ds_read_b128 v[212:215], v147 offset:5120
	ds_read_b128 v[216:219], v147 offset:6144
	ds_read_b128 v[220:223], v147 offset:7168
	global_load_lds_dwordx4 v[156:157], off
	v_lshl_add_u64 v[156:157], s[38:39], 0, v[138:139]
	s_add_i32 m0, s58, 0xe000
	s_nop 0
	global_load_lds_dwordx4 v[156:157], off
	s_waitcnt vmcnt(8)
	s_cmp_lg_u64 s[6:7], 0
	s_cbranch_scc1 .Llgk_218_0
	s_waitcnt lgkmcnt(0)
.Llgk_218_0:
	s_barrier
	s_setprio 1
	s_waitcnt lgkmcnt(0)
	v_mfma_f32_16x16x32_bf16 v[128:131], v[140:143], v[184:187], v[128:131]
	v_mfma_f32_16x16x32_bf16 v[124:127], v[152:155], v[184:187], v[124:127]
	v_mfma_f32_16x16x32_bf16 v[120:123], v[140:143], v[192:195], v[120:123]
	v_mfma_f32_16x16x32_bf16 v[112:115], v[152:155], v[192:195], v[112:115]
	v_mfma_f32_16x16x32_bf16 v[104:107], v[140:143], v[208:211], v[104:107]
	v_mfma_f32_16x16x32_bf16 v[96:99], v[152:155], v[208:211], v[96:99]
	v_mfma_f32_16x16x32_bf16 v[88:91], v[140:143], v[216:219], v[88:91]
	v_mfma_f32_16x16x32_bf16 v[80:83], v[152:155], v[216:219], v[80:83]
	v_mfma_f32_16x16x32_bf16 v[128:131], v[148:151], v[188:191], v[128:131]
	v_mfma_f32_16x16x32_bf16 v[124:127], v[164:167], v[188:191], v[124:127]
	v_mfma_f32_16x16x32_bf16 v[120:123], v[148:151], v[204:207], v[120:123]
	v_mfma_f32_16x16x32_bf16 v[112:115], v[164:167], v[204:207], v[112:115]
	v_mfma_f32_16x16x32_bf16 v[104:107], v[148:151], v[212:215], v[104:107]
	v_mfma_f32_16x16x32_bf16 v[96:99], v[164:167], v[212:215], v[96:99]
	v_mfma_f32_16x16x32_bf16 v[88:91], v[148:151], v[220:223], v[88:91]
	v_mfma_f32_16x16x32_bf16 v[80:83], v[164:167], v[220:223], v[80:83]
	s_setprio 0
	s_setprio 1
	v_mfma_f32_16x16x32_bf16 v[116:119], v[168:171], v[184:187], v[116:119]
	v_mfma_f32_16x16x32_bf16 v[108:111], v[176:179], v[184:187], v[108:111]
	v_mfma_f32_16x16x32_bf16 v[100:103], v[168:171], v[192:195], v[100:103]
	v_mfma_f32_16x16x32_bf16 v[92:95], v[176:179], v[192:195], v[92:95]
	v_mfma_f32_16x16x32_bf16 v[84:87], v[168:171], v[208:211], v[84:87]
	v_mfma_f32_16x16x32_bf16 v[76:79], v[176:179], v[208:211], v[76:79]
	v_mfma_f32_16x16x32_bf16 v[72:75], v[168:171], v[216:219], v[72:75]
	v_mfma_f32_16x16x32_bf16 v[68:71], v[176:179], v[216:219], v[68:71]
	v_mfma_f32_16x16x32_bf16 v[116:119], v[172:175], v[188:191], v[116:119]
	v_mfma_f32_16x16x32_bf16 v[108:111], v[180:183], v[188:191], v[108:111]
	v_mfma_f32_16x16x32_bf16 v[100:103], v[172:175], v[204:207], v[100:103]
	v_mfma_f32_16x16x32_bf16 v[92:95], v[180:183], v[204:207], v[92:95]
	s_setprio 2
	s_barrier
	v_mfma_f32_16x16x32_bf16 v[84:87], v[172:175], v[212:215], v[84:87]
	v_mfma_f32_16x16x32_bf16 v[76:79], v[180:183], v[212:215], v[76:79]
	v_mfma_f32_16x16x32_bf16 v[72:75], v[172:175], v[220:223], v[72:75]
	v_mfma_f32_16x16x32_bf16 v[68:71], v[180:183], v[220:223], v[68:71]
	s_setprio 0
	s_add_i32 s30, s31, s53
	v_lshl_add_u64 v[156:157], s[40:41], 0, v[2:3]
	s_mov_b32 m0, s30
	ds_read_b128 v[184:187], v147 offset:16384
	ds_read_b128 v[188:191], v147 offset:17408
	ds_read_b128 v[192:195], v147 offset:18432
	ds_read_b128 v[204:207], v147 offset:19456
	ds_read_b128 v[208:211], v147 offset:20480
	ds_read_b128 v[212:215], v147 offset:21504
	ds_read_b128 v[216:219], v147 offset:22528
	ds_read_b128 v[220:223], v147 offset:23552
	global_load_lds_dwordx4 v[156:157], off
	s_add_i32 m0, s30, 0x2000
	s_add_u32 s30, s40, 0x80000
	v_lshl_add_u64 v[196:197], s[40:41], 0, v[0:1]
	s_addc_u32 s31, s41, 0
	s_add_i32 s27, s27, s53
	global_load_lds_dwordx4 v[196:197], off
	v_lshl_add_u64 v[224:225], s[30:31], 0, v[2:3]
	s_mov_b32 m0, s27
	v_lshl_add_u64 v[226:227], s[42:43], 0, v[132:133]
	global_load_lds_dwordx4 v[224:225], off
	v_lshl_add_u64 v[224:225], s[30:31], 0, v[0:1]
	s_add_i32 m0, s27, 0x2000
	s_nop 0
	global_load_lds_dwordx4 v[224:225], off
	v_lshl_add_u64 v[224:225], s[42:43], 0, v[134:135]
	s_mov_b32 m0, s58
	s_nop 0
	global_load_lds_dwordx4 v[224:225], off
	s_mov_b32 m0, s59
	s_nop 0
	global_load_lds_dwordx4 v[226:227], off
	s_waitcnt vmcnt(8)
	s_cmp_lg_u64 s[6:7], 0
	s_cbranch_scc1 .Llgk_218_1
	s_waitcnt lgkmcnt(0)
; #define PG8_STAGE(bufoff, gbase, voff) do { _Pragma("unroll") for (int _i = 0; _i < 2; ++_i) \
;         __builtin_amdgcn_global_load_lds((const unsigned*)((const char*)(gbase) + (voff)[_i]), (LAS unsigned*)(lds + (bufoff) + ldsw + _i * 8192), 16, 0, 0); } while (0)
; #define PG8_LDA(dst, b, h) do { _Pragma("unroll") for (int m = 0; m < 4; ++m) _Pragma("unroll") for (int k = 0; k < 2; ++k) dst[m][k] = *(const LAS bf16x8*)(lds + PG8_SA(b, h) + aoff + m * 2048 + k * 1024); } while (0)
; #define PG8_LDB(dst, b, h) do { _Pragma("unroll") for (int n = 0; n < 2; ++n) _Pragma("unroll") for (int k = 0; k < 2; ++k) dst[n][k] = *(const LAS bf16x8*)(lds + PG8_SB(b, h) + boff + n * 2048 + k * 1024); } while (0)
; #define PG8_MMA(ai, bj, At, Bt) do { __builtin_amdgcn_s_setprio(1); _Pragma("unroll") for (int m = 0; m < 4; ++m) _Pragma("unroll") for (int n = 0; n < 2; ++n) _Pragma("unroll") for (int k = 0; k < 2; ++k) \
;         acc[ai][bj][m][n] = __builtin_amdgcn_mfma_f32_16x16x32_bf16(Bt[n][k], At[m][k], acc[ai][bj][m][n], 0, 0, 0); __builtin_amdgcn_s_setprio(0); } while (0)
; #define PG8_WAIT_V(n) asm volatile("s_waitcnt vmcnt(" #n ")" ::: "memory")
; #define PG8_WAIT_L(n) asm volatile("s_waitcnt lgkmcnt(" #n ")" ::: "memory")
; #define PG8_BAR __builtin_amdgcn_s_barrier()
; #define PG8_SCHED __builtin_amdgcn_sched_barrier(0)
; template <class Epi, class Sched, bool ALIGN_EPI = true>
; __device__ __forceinline__ void gemm_phase(LAS unsigned char* lds, const Gemm g, const Sched& S, const Epi& E) {
;     ...
;             PG8_WAIT_V(8); PG8_WAIT_L(0); PG8_BAR; PG8_MMA(1, 0, At, B0); PG8_MMA(1, 1, At, B1); PG8_BAR; PG8_SCHED;
;             PG8_LDB(B0, 1, 0); PG8_LDB(B1, 1, 1); PG8_SCHED; PG8_LDA(At, 1, 0); PG8_STAGE(PG8_SA(0, 1), a2 + hA, voffA);
;             PG8_WAIT_V(8); PG8_WAIT_L(0); PG8_BAR; PG8_MMA(0, 0, At, B0); PG8_MMA(0, 1, At, B1); PG8_BAR; PG8_SCHED;
.Llgk_218_1:
	s_barrier
	s_setprio 1
	s_waitcnt lgkmcnt(0)
	v_mfma_f32_16x16x32_bf16 v[64:67], v[140:143], v[184:187], v[64:67]
	v_mfma_f32_16x16x32_bf16 v[60:63], v[152:155], v[184:187], v[60:63]
	v_mfma_f32_16x16x32_bf16 v[56:59], v[140:143], v[192:195], v[56:59]
	v_mfma_f32_16x16x32_bf16 v[48:51], v[152:155], v[192:195], v[48:51]
	v_mfma_f32_16x16x32_bf16 v[40:43], v[140:143], v[208:211], v[40:43]
	v_mfma_f32_16x16x32_bf16 v[32:35], v[152:155], v[208:211], v[32:35]
	v_mfma_f32_16x16x32_bf16 v[24:27], v[140:143], v[216:219], v[24:27]
	v_mfma_f32_16x16x32_bf16 v[16:19], v[152:155], v[216:219], v[16:19]
	v_mfma_f32_16x16x32_bf16 v[64:67], v[148:151], v[188:191], v[64:67]
	v_mfma_f32_16x16x32_bf16 v[60:63], v[164:167], v[188:191], v[60:63]
	v_mfma_f32_16x16x32_bf16 v[56:59], v[148:151], v[204:207], v[56:59]
	v_mfma_f32_16x16x32_bf16 v[48:51], v[164:167], v[204:207], v[48:51]
	v_mfma_f32_16x16x32_bf16 v[40:43], v[148:151], v[212:215], v[40:43]
	v_mfma_f32_16x16x32_bf16 v[32:35], v[164:167], v[212:215], v[32:35]
	v_mfma_f32_16x16x32_bf16 v[24:27], v[148:151], v[220:223], v[24:27]
	v_mfma_f32_16x16x32_bf16 v[16:19], v[164:167], v[220:223], v[16:19]
	s_setprio 0
	s_setprio 1
	v_mfma_f32_16x16x32_bf16 v[52:55], v[168:171], v[184:187], v[52:55]
	v_mfma_f32_16x16x32_bf16 v[44:47], v[176:179], v[184:187], v[44:47]
	v_mfma_f32_16x16x32_bf16 v[36:39], v[168:171], v[192:195], v[36:39]
	v_mfma_f32_16x16x32_bf16 v[28:31], v[176:179], v[192:195], v[28:31]
	v_mfma_f32_16x16x32_bf16 v[20:23], v[168:171], v[208:211], v[20:23]
	v_mfma_f32_16x16x32_bf16 v[12:15], v[176:179], v[208:211], v[12:15]
	v_mfma_f32_16x16x32_bf16 v[8:11], v[168:171], v[216:219], v[8:11]
	v_mfma_f32_16x16x32_bf16 v[4:7], v[176:179], v[216:219], v[4:7]
	v_mfma_f32_16x16x32_bf16 v[52:55], v[172:175], v[188:191], v[52:55]
	v_mfma_f32_16x16x32_bf16 v[44:47], v[180:183], v[188:191], v[44:47]
	v_mfma_f32_16x16x32_bf16 v[36:39], v[172:175], v[204:207], v[36:39]
	v_mfma_f32_16x16x32_bf16 v[28:31], v[180:183], v[204:207], v[28:31]
	s_setprio 2
	s_barrier
	v_mfma_f32_16x16x32_bf16 v[20:23], v[172:175], v[212:215], v[20:23]
	v_mfma_f32_16x16x32_bf16 v[12:15], v[180:183], v[212:215], v[12:15]
	v_mfma_f32_16x16x32_bf16 v[8:11], v[172:175], v[220:223], v[8:11]
	v_mfma_f32_16x16x32_bf16 v[4:7], v[180:183], v[220:223], v[4:7]
	s_setprio 0
	s_add_i32 s27, 0, 0x18000
	v_add_u32_e32 v158, s27, v145
	s_add_i32 s65, 0, 0x1c000
	ds_read_b128 v[140:143], v158
	ds_read_b128 v[148:151], v158 offset:1024
	ds_read_b128 v[152:155], v158 offset:2048
	ds_read_b128 v[164:167], v158 offset:3072
	v_add_u32_e32 v158, s65, v145
	ds_read_b128 v[168:171], v158
	ds_read_b128 v[172:175], v158 offset:1024
	ds_read_b128 v[176:179], v158 offset:2048
	ds_read_b128 v[180:183], v158 offset:3072
	s_add_u32 s30, s42, 0x80000
	s_addc_u32 s31, s43, 0
	s_mov_b32 m0, s60
	v_lshl_add_u64 v[228:229], s[30:31], 0, v[134:135]
	ds_read_b128 v[184:187], v147 offset:32768
	ds_read_b128 v[188:191], v147 offset:33792
	ds_read_b128 v[192:195], v147 offset:34816
	ds_read_b128 v[204:207], v147 offset:35840
	ds_read_b128 v[208:211], v147 offset:36864
	ds_read_b128 v[212:215], v147 offset:37888
	ds_read_b128 v[216:219], v147 offset:38912
	ds_read_b128 v[220:223], v147 offset:39936
	global_load_lds_dwordx4 v[228:229], off
	v_lshl_add_u64 v[228:229], s[30:31], 0, v[132:133]
	s_mov_b32 m0, s61
	s_nop 0
	global_load_lds_dwordx4 v[228:229], off
	s_waitcnt vmcnt(8)
	s_cmp_lg_u64 s[6:7], 0
	s_cbranch_scc1 .Llgk_218_2
	s_waitcnt lgkmcnt(0)
; #define PG8_STAGE(bufoff, gbase, voff) do { _Pragma("unroll") for (int _i = 0; _i < 2; ++_i) \
;         __builtin_amdgcn_global_load_lds((const unsigned*)((const char*)(gbase) + (voff)[_i]), (LAS unsigned*)(lds + (bufoff) + ldsw + _i * 8192), 16, 0, 0); } while (0)
; #define PG8_LDA(dst, b, h) do { _Pragma("unroll") for (int m = 0; m < 4; ++m) _Pragma("unroll") for (int k = 0; k < 2; ++k) dst[m][k] = *(const LAS bf16x8*)(lds + PG8_SA(b, h) + aoff + m * 2048 + k * 1024); } while (0)
; #define PG8_MMA(ai, bj, At, Bt) do { __builtin_amdgcn_s_setprio(1); _Pragma("unroll") for (int m = 0; m < 4; ++m) _Pragma("unroll") for (int n = 0; n < 2; ++n) _Pragma("unroll") for (int k = 0; k < 2; ++k) \
;         acc[ai][bj][m][n] = __builtin_amdgcn_mfma_f32_16x16x32_bf16(Bt[n][k], At[m][k], acc[ai][bj][m][n], 0, 0, 0); __builtin_amdgcn_s_setprio(0); } while (0)
; #define PG8_WAIT_V(n) asm volatile("s_waitcnt vmcnt(" #n ")" ::: "memory")
; #define PG8_WAIT_L(n) asm volatile("s_waitcnt lgkmcnt(" #n ")" ::: "memory")
; #define PG8_BAR __builtin_amdgcn_s_barrier()
; #define PG8_SCHED __builtin_amdgcn_sched_barrier(0)
; template <class Epi, class Sched, bool ALIGN_EPI = true>
; __device__ __forceinline__ void gemm_phase(LAS unsigned char* lds, const Gemm g, const Sched& S, const Epi& E) {
;     ...
;             PG8_WAIT_V(8); PG8_WAIT_L(0); PG8_BAR; PG8_MMA(0, 0, At, B0); PG8_MMA(0, 1, At, B1); PG8_BAR; PG8_SCHED;
;             PG8_LDA(At, 1, 1); PG8_STAGE(PG8_SB(1, 0), b3, voffB); PG8_STAGE(PG8_SB(1, 1), b3 + hB, voffB); PG8_STAGE(PG8_SA(1, 0), a3, voffA);
;             PG8_WAIT_V(8); PG8_WAIT_L(0); PG8_BAR; PG8_MMA(1, 0, At, B0); PG8_MMA(1, 1, At, B1); PG8_BAR; PG8_SCHED;
;         }
;         if constexpr (ALIGN_EPI) { if (wr == 0) PG8_BAR; }
.Llgk_218_2:
	s_barrier
	s_setprio 1
	s_waitcnt lgkmcnt(0)
	v_mfma_f32_16x16x32_bf16 v[128:131], v[140:143], v[184:187], v[128:131]
	v_mfma_f32_16x16x32_bf16 v[124:127], v[152:155], v[184:187], v[124:127]
	v_mfma_f32_16x16x32_bf16 v[120:123], v[140:143], v[192:195], v[120:123]
	v_mfma_f32_16x16x32_bf16 v[112:115], v[152:155], v[192:195], v[112:115]
	v_mfma_f32_16x16x32_bf16 v[104:107], v[140:143], v[208:211], v[104:107]
	v_mfma_f32_16x16x32_bf16 v[96:99], v[152:155], v[208:211], v[96:99]
	v_mfma_f32_16x16x32_bf16 v[88:91], v[140:143], v[216:219], v[88:91]
	v_mfma_f32_16x16x32_bf16 v[80:83], v[152:155], v[216:219], v[80:83]
	v_mfma_f32_16x16x32_bf16 v[128:131], v[148:151], v[188:191], v[128:131]
	v_mfma_f32_16x16x32_bf16 v[124:127], v[164:167], v[188:191], v[124:127]
	v_mfma_f32_16x16x32_bf16 v[120:123], v[148:151], v[204:207], v[120:123]
	v_mfma_f32_16x16x32_bf16 v[112:115], v[164:167], v[204:207], v[112:115]
	v_mfma_f32_16x16x32_bf16 v[104:107], v[148:151], v[212:215], v[104:107]
	v_mfma_f32_16x16x32_bf16 v[96:99], v[164:167], v[212:215], v[96:99]
	v_mfma_f32_16x16x32_bf16 v[88:91], v[148:151], v[220:223], v[88:91]
	v_mfma_f32_16x16x32_bf16 v[80:83], v[164:167], v[220:223], v[80:83]
	s_setprio 0
	s_setprio 1
	v_mfma_f32_16x16x32_bf16 v[116:119], v[168:171], v[184:187], v[116:119]
	v_mfma_f32_16x16x32_bf16 v[108:111], v[176:179], v[184:187], v[108:111]
	v_mfma_f32_16x16x32_bf16 v[100:103], v[168:171], v[192:195], v[100:103]
	v_mfma_f32_16x16x32_bf16 v[92:95], v[176:179], v[192:195], v[92:95]
	v_mfma_f32_16x16x32_bf16 v[84:87], v[168:171], v[208:211], v[84:87]
	v_mfma_f32_16x16x32_bf16 v[76:79], v[176:179], v[208:211], v[76:79]
	v_mfma_f32_16x16x32_bf16 v[72:75], v[168:171], v[216:219], v[72:75]
	v_mfma_f32_16x16x32_bf16 v[68:71], v[176:179], v[216:219], v[68:71]
	v_mfma_f32_16x16x32_bf16 v[116:119], v[172:175], v[188:191], v[116:119]
	v_mfma_f32_16x16x32_bf16 v[108:111], v[180:183], v[188:191], v[108:111]
	v_mfma_f32_16x16x32_bf16 v[100:103], v[172:175], v[204:207], v[100:103]
	v_mfma_f32_16x16x32_bf16 v[92:95], v[180:183], v[204:207], v[92:95]
	s_setprio 2
	s_barrier
	v_mfma_f32_16x16x32_bf16 v[84:87], v[172:175], v[212:215], v[84:87]
	v_mfma_f32_16x16x32_bf16 v[76:79], v[180:183], v[212:215], v[76:79]
	v_mfma_f32_16x16x32_bf16 v[72:75], v[172:175], v[220:223], v[72:75]
	v_mfma_f32_16x16x32_bf16 v[68:71], v[180:183], v[220:223], v[68:71]
	s_setprio 0
	s_add_i32 s27, s27, s53
	v_lshl_add_u64 v[156:157], v[156:157], 0, s[86:87]
	s_mov_b32 m0, s27
	ds_read_b128 v[184:187], v147 offset:49152
	ds_read_b128 v[188:191], v147 offset:50176
	ds_read_b128 v[192:195], v147 offset:51200
	ds_read_b128 v[204:207], v147 offset:52224
	ds_read_b128 v[208:211], v147 offset:53248
	ds_read_b128 v[212:215], v147 offset:54272
	ds_read_b128 v[216:219], v147 offset:55296
	ds_read_b128 v[220:223], v147 offset:56320
	global_load_lds_dwordx4 v[156:157], off
	s_add_i32 m0, s27, 0x2000
	s_add_u32 s30, s40, 0x80080
	v_lshl_add_u64 v[156:157], v[196:197], 0, s[86:87]
	s_addc_u32 s31, s41, 0
	s_add_i32 s27, s65, s53
	global_load_lds_dwordx4 v[156:157], off
	v_lshl_add_u64 v[156:157], s[30:31], 0, v[2:3]
	s_mov_b32 m0, s27
	s_nop 0
	global_load_lds_dwordx4 v[156:157], off
	v_lshl_add_u64 v[156:157], s[30:31], 0, v[0:1]
	s_add_i32 m0, s27, 0x2000
	s_nop 0
	global_load_lds_dwordx4 v[156:157], off
	v_lshl_add_u64 v[156:157], v[224:225], 0, s[86:87]
	s_mov_b32 m0, s62
	s_nop 0
	global_load_lds_dwordx4 v[156:157], off
	v_lshl_add_u64 v[156:157], v[226:227], 0, s[86:87]
	s_mov_b32 m0, s63
	s_nop 0
	global_load_lds_dwordx4 v[156:157], off
	s_waitcnt vmcnt(8)
	s_cmp_lg_u64 s[6:7], 0
	s_cbranch_scc1 .Llgk_218_3
	s_waitcnt lgkmcnt(0)
.Llgk_218_3:
	s_barrier
	s_setprio 1
	s_waitcnt lgkmcnt(0)
	v_mfma_f32_16x16x32_bf16 v[64:67], v[140:143], v[184:187], v[64:67]
	v_mfma_f32_16x16x32_bf16 v[60:63], v[152:155], v[184:187], v[60:63]
	v_mfma_f32_16x16x32_bf16 v[56:59], v[140:143], v[192:195], v[56:59]
	v_mfma_f32_16x16x32_bf16 v[48:51], v[152:155], v[192:195], v[48:51]
	v_mfma_f32_16x16x32_bf16 v[40:43], v[140:143], v[208:211], v[40:43]
	v_mfma_f32_16x16x32_bf16 v[32:35], v[152:155], v[208:211], v[32:35]
	v_mfma_f32_16x16x32_bf16 v[24:27], v[140:143], v[216:219], v[24:27]
	v_mfma_f32_16x16x32_bf16 v[16:19], v[152:155], v[216:219], v[16:19]
	v_mfma_f32_16x16x32_bf16 v[64:67], v[148:151], v[188:191], v[64:67]
	v_mfma_f32_16x16x32_bf16 v[60:63], v[164:167], v[188:191], v[60:63]
	v_mfma_f32_16x16x32_bf16 v[56:59], v[148:151], v[204:207], v[56:59]
	v_mfma_f32_16x16x32_bf16 v[48:51], v[164:167], v[204:207], v[48:51]
	v_mfma_f32_16x16x32_bf16 v[40:43], v[148:151], v[212:215], v[40:43]
	v_mfma_f32_16x16x32_bf16 v[32:35], v[164:167], v[212:215], v[32:35]
	v_mfma_f32_16x16x32_bf16 v[24:27], v[148:151], v[220:223], v[24:27]
	v_mfma_f32_16x16x32_bf16 v[16:19], v[164:167], v[220:223], v[16:19]
	s_setprio 0
	s_setprio 1
	v_mfma_f32_16x16x32_bf16 v[52:55], v[168:171], v[184:187], v[52:55]
	v_mfma_f32_16x16x32_bf16 v[44:47], v[176:179], v[184:187], v[44:47]
	v_mfma_f32_16x16x32_bf16 v[36:39], v[168:171], v[192:195], v[36:39]
	v_mfma_f32_16x16x32_bf16 v[28:31], v[176:179], v[192:195], v[28:31]
	v_mfma_f32_16x16x32_bf16 v[20:23], v[168:171], v[208:211], v[20:23]
	v_mfma_f32_16x16x32_bf16 v[12:15], v[176:179], v[208:211], v[12:15]
	v_mfma_f32_16x16x32_bf16 v[8:11], v[168:171], v[216:219], v[8:11]
	v_mfma_f32_16x16x32_bf16 v[4:7], v[176:179], v[216:219], v[4:7]
	v_mfma_f32_16x16x32_bf16 v[52:55], v[172:175], v[188:191], v[52:55]
	v_mfma_f32_16x16x32_bf16 v[44:47], v[180:183], v[188:191], v[44:47]
	v_mfma_f32_16x16x32_bf16 v[36:39], v[172:175], v[204:207], v[36:39]
	v_mfma_f32_16x16x32_bf16 v[28:31], v[180:183], v[204:207], v[28:31]
	s_setprio 2
	s_barrier
	v_mfma_f32_16x16x32_bf16 v[20:23], v[172:175], v[212:215], v[20:23]
	v_mfma_f32_16x16x32_bf16 v[12:15], v[180:183], v[212:215], v[12:15]
	v_mfma_f32_16x16x32_bf16 v[8:11], v[172:175], v[220:223], v[8:11]
	v_mfma_f32_16x16x32_bf16 v[4:7], v[180:183], v[220:223], v[4:7]
	s_setprio 0
	s_add_i32 s26, s26, 2
	s_add_u32 s38, s38, 0x100
	s_addc_u32 s39, s39, 0
	s_add_u32 s24, s24, 0x100
	s_addc_u32 s25, s25, 0
	s_cmp_gt_u32 s26, 29
	s_cbranch_scc0 .LBB0_218
	s_and_b64 vcc, exec, s[6:7]
	s_cbranch_vccz .LBB0_221
	s_barrier

; #define PG8_STAGE(bufoff, gbase, voff) do { _Pragma("unroll") for (int _i = 0; _i < 2; ++_i) \
;         __builtin_amdgcn_global_load_lds((const unsigned*)((const char*)(gbase) + (voff)[_i]), (LAS unsigned*)(lds + (bufoff) + ldsw + _i * 8192), 16, 0, 0); } while (0)
; #define PG8_LDA(dst, b, h) do { _Pragma("unroll") for (int m = 0; m < 4; ++m) _Pragma("unroll") for (int k = 0; k < 2; ++k) dst[m][k] = *(const LAS bf16x8*)(lds + PG8_SA(b, h) + aoff + m * 2048 + k * 1024); } while (0)
; #define PG8_LDB(dst, b, h) do { _Pragma("unroll") for (int n = 0; n < 2; ++n) _Pragma("unroll") for (int k = 0; k < 2; ++k) dst[n][k] = *(const LAS bf16x8*)(lds + PG8_SB(b, h) + boff + n * 2048 + k * 1024); } while (0)
; #define PG8_MMA(ai, bj, At, Bt) do { __builtin_amdgcn_s_setprio(1); _Pragma("unroll") for (int m = 0; m < 4; ++m) _Pragma("unroll") for (int n = 0; n < 2; ++n) _Pragma("unroll") for (int k = 0; k < 2; ++k) \
;         acc[ai][bj][m][n] = __builtin_amdgcn_mfma_f32_16x16x32_bf16(Bt[n][k], At[m][k], acc[ai][bj][m][n], 0, 0, 0); __builtin_amdgcn_s_setprio(0); } while (0)
; #define PG8_WAIT_V(n) asm volatile("s_waitcnt vmcnt(" #n ")" ::: "memory")
; #define PG8_WAIT_L(n) asm volatile("s_waitcnt lgkmcnt(" #n ")" ::: "memory")
; #define PG8_BAR __builtin_amdgcn_s_barrier()
; #define PG8_SCHED __builtin_amdgcn_sched_barrier(0)
; template <class Epi, class Sched, bool ALIGN_EPI = true>
; __device__ __forceinline__ void gemm_phase(LAS unsigned char* lds, const Gemm g, const Sched& S, const Epi& E) {
;     ...
;             PG8_LDB(B0, 0, 0); PG8_LDB(B1, 0, 1); PG8_SCHED; PG8_LDA(At, 0, 0); PG8_STAGE(PG8_SA(1, 1), a1 + hA, voffA);
;             PG8_WAIT_V(8); PG8_WAIT_L(0); PG8_BAR; PG8_MMA(0, 0, At, B0); PG8_MMA(0, 1, At, B1); PG8_BAR; PG8_SCHED;
;             PG8_LDA(At, 0, 1); PG8_STAGE(PG8_SB(0, 0), b2, voffB); PG8_STAGE(PG8_SB(0, 1), b2 + hB, voffB); PG8_STAGE(PG8_SA(0, 0), a2, voffA);
;             PG8_WAIT_V(8); PG8_WAIT_L(0); PG8_BAR; PG8_MMA(1, 0, At, B0); PG8_MMA(1, 1, At, B1); PG8_BAR; PG8_SCHED;
.LBB0_667:
	s_add_u32 vcc_lo, s10, 0x100
	s_addc_u32 vcc_hi, s11, 0
	s_add_u32 s25, s18, s10
	s_addc_u32 s26, s19, s11
	s_add_i32 s27, 0, 0x10000
	s_cmp_eq_u32 s24, 28
	s_cselect_b32 s65, s16, s26
	s_cselect_b32 s26, 0, vcc_lo
	s_cselect_b32 s64, s17, s25
	s_cselect_b32 s25, 0, vcc_hi
	s_add_u32 s62, s14, s26
	v_add_u32_e32 v160, s27, v186
	s_addc_u32 s63, s15, s25
	s_add_i32 s25, 0, 0x14000
	ds_read_b128 v[136:139], v160
	ds_read_b128 v[140:143], v160 offset:1024
	ds_read_b128 v[144:147], v160 offset:2048
	ds_read_b128 v[170:173], v160 offset:3072
	v_add_u32_e32 v160, s25, v186
	ds_read_b128 v[174:177], v160
	ds_read_b128 v[178:181], v160 offset:1024
	ds_read_b128 v[182:185], v160 offset:2048
	ds_read_b128 v[208:211], v160 offset:3072
	v_lshl_add_u64 v[244:245], v[132:133], 0, s[10:11]
	s_add_i32 m0, s53, 0xc000
	ds_read_b128 v[212:215], v197
	ds_read_b128 v[216:219], v197 offset:1024
	ds_read_b128 v[220:223], v197 offset:2048
	ds_read_b128 v[224:227], v197 offset:3072
	ds_read_b128 v[228:231], v197 offset:4096
	ds_read_b128 v[232:235], v197 offset:5120
	ds_read_b128 v[236:239], v197 offset:6144
	ds_read_b128 v[240:243], v197 offset:7168
	global_load_lds_dwordx4 v[244:245], off
	v_lshl_add_u64 v[244:245], v[134:135], 0, s[10:11]
	s_add_i32 m0, s53, 0xe000
	s_nop 0
	global_load_lds_dwordx4 v[244:245], off
	s_waitcnt vmcnt(8)
	s_cmp_lg_u64 s[44:45], 0
	s_cbranch_scc1 .Llgk_667_0
	s_waitcnt lgkmcnt(0)
.Llgk_667_0:
	s_barrier
	s_setprio 1
	s_waitcnt lgkmcnt(0)
	v_mfma_f32_16x16x32_bf16 v[36:39], v[136:139], v[212:215], v[36:39]
	v_mfma_f32_16x16x32_bf16 v[40:43], v[144:147], v[212:215], v[40:43]
	v_mfma_f32_16x16x32_bf16 v[68:71], v[136:139], v[220:223], v[68:71]
	v_mfma_f32_16x16x32_bf16 v[72:75], v[144:147], v[220:223], v[72:75]
	v_mfma_f32_16x16x32_bf16 v[100:103], v[136:139], v[228:231], v[100:103]
	v_mfma_f32_16x16x32_bf16 v[104:107], v[144:147], v[228:231], v[104:107]
	v_mfma_f32_16x16x32_bf16 v[128:131], v[136:139], v[236:239], v[128:131]
	v_mfma_f32_16x16x32_bf16 v[124:127], v[144:147], v[236:239], v[124:127]
	v_mfma_f32_16x16x32_bf16 v[36:39], v[140:143], v[216:219], v[36:39]
	v_mfma_f32_16x16x32_bf16 v[40:43], v[170:173], v[216:219], v[40:43]
	v_mfma_f32_16x16x32_bf16 v[68:71], v[140:143], v[224:227], v[68:71]
	v_mfma_f32_16x16x32_bf16 v[72:75], v[170:173], v[224:227], v[72:75]
	v_mfma_f32_16x16x32_bf16 v[100:103], v[140:143], v[232:235], v[100:103]
	v_mfma_f32_16x16x32_bf16 v[104:107], v[170:173], v[232:235], v[104:107]
	v_mfma_f32_16x16x32_bf16 v[128:131], v[140:143], v[240:243], v[128:131]
	v_mfma_f32_16x16x32_bf16 v[124:127], v[170:173], v[240:243], v[124:127]
	s_setprio 0
	s_setprio 1
	v_mfma_f32_16x16x32_bf16 v[8:11], v[174:177], v[212:215], v[8:11]
	v_mfma_f32_16x16x32_bf16 v[4:7], v[182:185], v[212:215], v[4:7]
	v_mfma_f32_16x16x32_bf16 v[32:35], v[174:177], v[220:223], v[32:35]
	v_mfma_f32_16x16x32_bf16 v[28:31], v[182:185], v[220:223], v[28:31]
	v_mfma_f32_16x16x32_bf16 v[56:59], v[174:177], v[228:231], v[56:59]
	v_mfma_f32_16x16x32_bf16 v[52:55], v[182:185], v[228:231], v[52:55]
	v_mfma_f32_16x16x32_bf16 v[80:83], v[174:177], v[236:239], v[80:83]
	v_mfma_f32_16x16x32_bf16 v[76:79], v[182:185], v[236:239], v[76:79]
	v_mfma_f32_16x16x32_bf16 v[8:11], v[178:181], v[216:219], v[8:11]
	v_mfma_f32_16x16x32_bf16 v[4:7], v[208:211], v[216:219], v[4:7]
	v_mfma_f32_16x16x32_bf16 v[32:35], v[178:181], v[224:227], v[32:35]
	v_mfma_f32_16x16x32_bf16 v[28:31], v[208:211], v[224:227], v[28:31]
	s_setprio 2
	s_barrier
	v_mfma_f32_16x16x32_bf16 v[56:59], v[178:181], v[232:235], v[56:59]
	v_mfma_f32_16x16x32_bf16 v[52:55], v[208:211], v[232:235], v[52:55]
	v_mfma_f32_16x16x32_bf16 v[80:83], v[178:181], v[240:243], v[80:83]
	v_mfma_f32_16x16x32_bf16 v[76:79], v[208:211], v[240:243], v[76:79]
	s_setprio 0
	s_add_i32 s10, s27, s67
	v_lshl_add_u64 v[244:245], s[62:63], 0, v[2:3]
	s_mov_b32 m0, s10
	ds_read_b128 v[212:215], v197 offset:16384
	ds_read_b128 v[216:219], v197 offset:17408
	ds_read_b128 v[220:223], v197 offset:18432
	ds_read_b128 v[224:227], v197 offset:19456
	ds_read_b128 v[228:231], v197 offset:20480
	ds_read_b128 v[232:235], v197 offset:21504
	ds_read_b128 v[236:239], v197 offset:22528
	ds_read_b128 v[240:243], v197 offset:23552
	global_load_lds_dwordx4 v[244:245], off
	s_add_i32 m0, s10, 0x2000
	s_add_u32 s10, s62, 0x80000
	v_lshl_add_u64 v[246:247], s[62:63], 0, v[150:151]
	s_addc_u32 s11, s63, 0
	s_add_i32 s25, s25, s67
	global_load_lds_dwordx4 v[246:247], off
	v_lshl_add_u64 v[248:249], s[10:11], 0, v[2:3]
	s_mov_b32 m0, s25
	v_lshl_add_u64 v[160:161], s[64:65], 0, v[148:149]
	global_load_lds_dwordx4 v[248:249], off
	v_lshl_add_u64 v[248:249], s[10:11], 0, v[150:151]
	s_add_i32 m0, s25, 0x2000
	s_nop 0
	global_load_lds_dwordx4 v[248:249], off
	v_lshl_add_u64 v[248:249], s[64:65], 0, v[0:1]
	s_mov_b32 m0, s53
	s_nop 0
	global_load_lds_dwordx4 v[248:249], off
	s_mov_b32 m0, s66
	s_nop 0
	global_load_lds_dwordx4 v[160:161], off
	s_waitcnt vmcnt(8)
	s_cmp_lg_u64 s[44:45], 0
	s_cbranch_scc1 .Llgk_667_1
	s_waitcnt lgkmcnt(0)
; #define PG8_STAGE(bufoff, gbase, voff) do { _Pragma("unroll") for (int _i = 0; _i < 2; ++_i) \
;         __builtin_amdgcn_global_load_lds((const unsigned*)((const char*)(gbase) + (voff)[_i]), (LAS unsigned*)(lds + (bufoff) + ldsw + _i * 8192), 16, 0, 0); } while (0)
; #define PG8_LDA(dst, b, h) do { _Pragma("unroll") for (int m = 0; m < 4; ++m) _Pragma("unroll") for (int k = 0; k < 2; ++k) dst[m][k] = *(const LAS bf16x8*)(lds + PG8_SA(b, h) + aoff + m * 2048 + k * 1024); } while (0)
; #define PG8_LDB(dst, b, h) do { _Pragma("unroll") for (int n = 0; n < 2; ++n) _Pragma("unroll") for (int k = 0; k < 2; ++k) dst[n][k] = *(const LAS bf16x8*)(lds + PG8_SB(b, h) + boff + n * 2048 + k * 1024); } while (0)
; #define PG8_MMA(ai, bj, At, Bt) do { __builtin_amdgcn_s_setprio(1); _Pragma("unroll") for (int m = 0; m < 4; ++m) _Pragma("unroll") for (int n = 0; n < 2; ++n) _Pragma("unroll") for (int k = 0; k < 2; ++k) \
;         acc[ai][bj][m][n] = __builtin_amdgcn_mfma_f32_16x16x32_bf16(Bt[n][k], At[m][k], acc[ai][bj][m][n], 0, 0, 0); __builtin_amdgcn_s_setprio(0); } while (0)
; #define PG8_WAIT_V(n) asm volatile("s_waitcnt vmcnt(" #n ")" ::: "memory")
; #define PG8_WAIT_L(n) asm volatile("s_waitcnt lgkmcnt(" #n ")" ::: "memory")
; #define PG8_BAR __builtin_amdgcn_s_barrier()
; #define PG8_SCHED __builtin_amdgcn_sched_barrier(0)
; template <class Epi, class Sched, bool ALIGN_EPI = true>
; __device__ __forceinline__ void gemm_phase(LAS unsigned char* lds, const Gemm g, const Sched& S, const Epi& E) {
;     ...
;             PG8_WAIT_V(8); PG8_WAIT_L(0); PG8_BAR; PG8_MMA(1, 0, At, B0); PG8_MMA(1, 1, At, B1); PG8_BAR; PG8_SCHED;
;             PG8_LDB(B0, 1, 0); PG8_LDB(B1, 1, 1); PG8_SCHED; PG8_LDA(At, 1, 0); PG8_STAGE(PG8_SA(0, 1), a2 + hA, voffA);
;             PG8_WAIT_V(8); PG8_WAIT_L(0); PG8_BAR; PG8_MMA(0, 0, At, B0); PG8_MMA(0, 1, At, B1); PG8_BAR; PG8_SCHED;
.Llgk_667_1:
	s_barrier
	s_setprio 1
	s_waitcnt lgkmcnt(0)
	v_mfma_f32_16x16x32_bf16 v[120:123], v[136:139], v[212:215], v[120:123]
	v_mfma_f32_16x16x32_bf16 v[116:119], v[144:147], v[212:215], v[116:119]
	v_mfma_f32_16x16x32_bf16 v[96:99], v[136:139], v[220:223], v[96:99]
	v_mfma_f32_16x16x32_bf16 v[92:95], v[144:147], v[220:223], v[92:95]
	v_mfma_f32_16x16x32_bf16 v[64:67], v[136:139], v[228:231], v[64:67]
	v_mfma_f32_16x16x32_bf16 v[60:63], v[144:147], v[228:231], v[60:63]
	v_mfma_f32_16x16x32_bf16 v[24:27], v[136:139], v[236:239], v[24:27]
	v_mfma_f32_16x16x32_bf16 v[20:23], v[144:147], v[236:239], v[20:23]
	v_mfma_f32_16x16x32_bf16 v[120:123], v[140:143], v[216:219], v[120:123]
	v_mfma_f32_16x16x32_bf16 v[116:119], v[170:173], v[216:219], v[116:119]
	v_mfma_f32_16x16x32_bf16 v[96:99], v[140:143], v[224:227], v[96:99]
	v_mfma_f32_16x16x32_bf16 v[92:95], v[170:173], v[224:227], v[92:95]
	v_mfma_f32_16x16x32_bf16 v[64:67], v[140:143], v[232:235], v[64:67]
	v_mfma_f32_16x16x32_bf16 v[60:63], v[170:173], v[232:235], v[60:63]
	v_mfma_f32_16x16x32_bf16 v[24:27], v[140:143], v[240:243], v[24:27]
	v_mfma_f32_16x16x32_bf16 v[20:23], v[170:173], v[240:243], v[20:23]
	s_setprio 0
	s_setprio 1
	v_mfma_f32_16x16x32_bf16 v[112:115], v[174:177], v[212:215], v[112:115]
	v_mfma_f32_16x16x32_bf16 v[108:111], v[182:185], v[212:215], v[108:111]
	v_mfma_f32_16x16x32_bf16 v[88:91], v[174:177], v[220:223], v[88:91]
	v_mfma_f32_16x16x32_bf16 v[84:87], v[182:185], v[220:223], v[84:87]
	v_mfma_f32_16x16x32_bf16 v[48:51], v[174:177], v[228:231], v[48:51]
	v_mfma_f32_16x16x32_bf16 v[44:47], v[182:185], v[228:231], v[44:47]
	v_mfma_f32_16x16x32_bf16 v[16:19], v[174:177], v[236:239], v[16:19]
	v_mfma_f32_16x16x32_bf16 v[12:15], v[182:185], v[236:239], v[12:15]
	v_mfma_f32_16x16x32_bf16 v[112:115], v[178:181], v[216:219], v[112:115]
	v_mfma_f32_16x16x32_bf16 v[108:111], v[208:211], v[216:219], v[108:111]
	v_mfma_f32_16x16x32_bf16 v[88:91], v[178:181], v[224:227], v[88:91]
	v_mfma_f32_16x16x32_bf16 v[84:87], v[208:211], v[224:227], v[84:87]
	s_setprio 2
	s_barrier
	v_mfma_f32_16x16x32_bf16 v[48:51], v[178:181], v[232:235], v[48:51]
	v_mfma_f32_16x16x32_bf16 v[44:47], v[208:211], v[232:235], v[44:47]
	v_mfma_f32_16x16x32_bf16 v[16:19], v[178:181], v[240:243], v[16:19]
	v_mfma_f32_16x16x32_bf16 v[12:15], v[208:211], v[240:243], v[12:15]
	s_setprio 0
	s_add_i32 s25, 0, 0x18000
	v_add_u32_e32 v162, s25, v186
	s_add_i32 s26, 0, 0x1c000
	ds_read_b128 v[136:139], v162
	ds_read_b128 v[140:143], v162 offset:1024
	ds_read_b128 v[144:147], v162 offset:2048
	ds_read_b128 v[170:173], v162 offset:3072
	v_add_u32_e32 v162, s26, v186
	ds_read_b128 v[174:177], v162
	ds_read_b128 v[178:181], v162 offset:1024
	ds_read_b128 v[182:185], v162 offset:2048
	ds_read_b128 v[208:211], v162 offset:3072
	s_add_u32 s10, s64, 0x80000
	s_addc_u32 s11, s65, 0
	s_mov_b32 m0, s75
	v_lshl_add_u64 v[162:163], s[10:11], 0, v[0:1]
	ds_read_b128 v[212:215], v197 offset:32768
	ds_read_b128 v[216:219], v197 offset:33792
	ds_read_b128 v[220:223], v197 offset:34816
	ds_read_b128 v[224:227], v197 offset:35840
	ds_read_b128 v[228:231], v197 offset:36864
	ds_read_b128 v[232:235], v197 offset:37888
	ds_read_b128 v[236:239], v197 offset:38912
	ds_read_b128 v[240:243], v197 offset:39936
	global_load_lds_dwordx4 v[162:163], off
	v_lshl_add_u64 v[162:163], s[10:11], 0, v[148:149]
	s_mov_b32 m0, s76
	s_nop 0
	global_load_lds_dwordx4 v[162:163], off
	s_waitcnt vmcnt(8)
	s_cmp_lg_u64 s[44:45], 0
	s_cbranch_scc1 .Llgk_667_2
	s_waitcnt lgkmcnt(0)
; #define PG8_STAGE(bufoff, gbase, voff) do { _Pragma("unroll") for (int _i = 0; _i < 2; ++_i) \
;         __builtin_amdgcn_global_load_lds((const unsigned*)((const char*)(gbase) + (voff)[_i]), (LAS unsigned*)(lds + (bufoff) + ldsw + _i * 8192), 16, 0, 0); } while (0)
; #define PG8_LDA(dst, b, h) do { _Pragma("unroll") for (int m = 0; m < 4; ++m) _Pragma("unroll") for (int k = 0; k < 2; ++k) dst[m][k] = *(const LAS bf16x8*)(lds + PG8_SA(b, h) + aoff + m * 2048 + k * 1024); } while (0)
; #define PG8_MMA(ai, bj, At, Bt) do { __builtin_amdgcn_s_setprio(1); _Pragma("unroll") for (int m = 0; m < 4; ++m) _Pragma("unroll") for (int n = 0; n < 2; ++n) _Pragma("unroll") for (int k = 0; k < 2; ++k) \
;         acc[ai][bj][m][n] = __builtin_amdgcn_mfma_f32_16x16x32_bf16(Bt[n][k], At[m][k], acc[ai][bj][m][n], 0, 0, 0); __builtin_amdgcn_s_setprio(0); } while (0)
; #define PG8_WAIT_V(n) asm volatile("s_waitcnt vmcnt(" #n ")" ::: "memory")
; #define PG8_WAIT_L(n) asm volatile("s_waitcnt lgkmcnt(" #n ")" ::: "memory")
; #define PG8_BAR __builtin_amdgcn_s_barrier()
; #define PG8_SCHED __builtin_amdgcn_sched_barrier(0)
; template <class Epi, class Sched, bool ALIGN_EPI = true>
; __device__ __forceinline__ void gemm_phase(LAS unsigned char* lds, const Gemm g, const Sched& S, const Epi& E) {
;     ...
;             PG8_WAIT_V(8); PG8_WAIT_L(0); PG8_BAR; PG8_MMA(0, 0, At, B0); PG8_MMA(0, 1, At, B1); PG8_BAR; PG8_SCHED;
;             PG8_LDA(At, 1, 1); PG8_STAGE(PG8_SB(1, 0), b3, voffB); PG8_STAGE(PG8_SB(1, 1), b3 + hB, voffB); PG8_STAGE(PG8_SA(1, 0), a3, voffA);
;             PG8_WAIT_V(8); PG8_WAIT_L(0); PG8_BAR; PG8_MMA(1, 0, At, B0); PG8_MMA(1, 1, At, B1); PG8_BAR; PG8_SCHED;
;         }
;         if constexpr (ALIGN_EPI) { if (wr == 0) PG8_BAR; }
.Llgk_667_2:
	s_barrier
	s_setprio 1
	s_waitcnt lgkmcnt(0)
	v_mfma_f32_16x16x32_bf16 v[36:39], v[136:139], v[212:215], v[36:39]
	v_mfma_f32_16x16x32_bf16 v[40:43], v[144:147], v[212:215], v[40:43]
	v_mfma_f32_16x16x32_bf16 v[68:71], v[136:139], v[220:223], v[68:71]
	v_mfma_f32_16x16x32_bf16 v[72:75], v[144:147], v[220:223], v[72:75]
	v_mfma_f32_16x16x32_bf16 v[100:103], v[136:139], v[228:231], v[100:103]
	v_mfma_f32_16x16x32_bf16 v[104:107], v[144:147], v[228:231], v[104:107]
	v_mfma_f32_16x16x32_bf16 v[128:131], v[136:139], v[236:239], v[128:131]
	v_mfma_f32_16x16x32_bf16 v[124:127], v[144:147], v[236:239], v[124:127]
	v_mfma_f32_16x16x32_bf16 v[36:39], v[140:143], v[216:219], v[36:39]
	v_mfma_f32_16x16x32_bf16 v[40:43], v[170:173], v[216:219], v[40:43]
	v_mfma_f32_16x16x32_bf16 v[68:71], v[140:143], v[224:227], v[68:71]
	v_mfma_f32_16x16x32_bf16 v[72:75], v[170:173], v[224:227], v[72:75]
	v_mfma_f32_16x16x32_bf16 v[100:103], v[140:143], v[232:235], v[100:103]
	v_mfma_f32_16x16x32_bf16 v[104:107], v[170:173], v[232:235], v[104:107]
	v_mfma_f32_16x16x32_bf16 v[128:131], v[140:143], v[240:243], v[128:131]
	v_mfma_f32_16x16x32_bf16 v[124:127], v[170:173], v[240:243], v[124:127]
	s_setprio 0
	s_setprio 1
	v_mfma_f32_16x16x32_bf16 v[8:11], v[174:177], v[212:215], v[8:11]
	v_mfma_f32_16x16x32_bf16 v[4:7], v[182:185], v[212:215], v[4:7]
	v_mfma_f32_16x16x32_bf16 v[32:35], v[174:177], v[220:223], v[32:35]
	v_mfma_f32_16x16x32_bf16 v[28:31], v[182:185], v[220:223], v[28:31]
	v_mfma_f32_16x16x32_bf16 v[56:59], v[174:177], v[228:231], v[56:59]
	v_mfma_f32_16x16x32_bf16 v[52:55], v[182:185], v[228:231], v[52:55]
	v_mfma_f32_16x16x32_bf16 v[80:83], v[174:177], v[236:239], v[80:83]
	v_mfma_f32_16x16x32_bf16 v[76:79], v[182:185], v[236:239], v[76:79]
	v_mfma_f32_16x16x32_bf16 v[8:11], v[178:181], v[216:219], v[8:11]
	v_mfma_f32_16x16x32_bf16 v[4:7], v[208:211], v[216:219], v[4:7]
	v_mfma_f32_16x16x32_bf16 v[32:35], v[178:181], v[224:227], v[32:35]
	v_mfma_f32_16x16x32_bf16 v[28:31], v[208:211], v[224:227], v[28:31]
	s_setprio 2
	s_barrier
	v_mfma_f32_16x16x32_bf16 v[56:59], v[178:181], v[232:235], v[56:59]
	v_mfma_f32_16x16x32_bf16 v[52:55], v[208:211], v[232:235], v[52:55]
	v_mfma_f32_16x16x32_bf16 v[80:83], v[178:181], v[240:243], v[80:83]
	v_mfma_f32_16x16x32_bf16 v[76:79], v[208:211], v[240:243], v[76:79]
	s_setprio 0
	s_add_i32 s10, s25, s67
	v_lshl_add_u64 v[162:163], v[244:245], 0, s[86:87]
	s_mov_b32 m0, s10
	ds_read_b128 v[212:215], v197 offset:49152
	ds_read_b128 v[216:219], v197 offset:50176
	ds_read_b128 v[220:223], v197 offset:51200
	ds_read_b128 v[224:227], v197 offset:52224
	ds_read_b128 v[228:231], v197 offset:53248
	ds_read_b128 v[232:235], v197 offset:54272
	ds_read_b128 v[236:239], v197 offset:55296
	ds_read_b128 v[240:243], v197 offset:56320
	global_load_lds_dwordx4 v[162:163], off
	s_add_i32 m0, s10, 0x2000
	s_add_u32 s10, s62, 0x80080
	v_lshl_add_u64 v[162:163], v[246:247], 0, s[86:87]
	s_addc_u32 s11, s63, 0
	s_add_i32 s25, s26, s67
	global_load_lds_dwordx4 v[162:163], off
	v_lshl_add_u64 v[162:163], s[10:11], 0, v[2:3]
	s_mov_b32 m0, s25
	v_lshl_add_u64 v[160:161], v[160:161], 0, s[86:87]
	global_load_lds_dwordx4 v[162:163], off
	v_lshl_add_u64 v[162:163], s[10:11], 0, v[150:151]
	s_add_i32 m0, s25, 0x2000
	s_nop 0
	global_load_lds_dwordx4 v[162:163], off
	v_lshl_add_u64 v[162:163], v[248:249], 0, s[86:87]
	s_mov_b32 m0, s79
	s_nop 0
	global_load_lds_dwordx4 v[162:163], off
	s_mov_b32 m0, s80
	s_nop 0
	global_load_lds_dwordx4 v[160:161], off
	s_waitcnt vmcnt(8)
	s_cmp_lg_u64 s[44:45], 0
	s_cbranch_scc1 .Llgk_667_3
	s_waitcnt lgkmcnt(0)
.Llgk_667_3:
	s_barrier
	s_setprio 1
	s_waitcnt lgkmcnt(0)
	v_mfma_f32_16x16x32_bf16 v[120:123], v[136:139], v[212:215], v[120:123]
	v_mfma_f32_16x16x32_bf16 v[116:119], v[144:147], v[212:215], v[116:119]
	v_mfma_f32_16x16x32_bf16 v[96:99], v[136:139], v[220:223], v[96:99]
	v_mfma_f32_16x16x32_bf16 v[92:95], v[144:147], v[220:223], v[92:95]
	v_mfma_f32_16x16x32_bf16 v[64:67], v[136:139], v[228:231], v[64:67]
	v_mfma_f32_16x16x32_bf16 v[60:63], v[144:147], v[228:231], v[60:63]
	v_mfma_f32_16x16x32_bf16 v[24:27], v[136:139], v[236:239], v[24:27]
	v_mfma_f32_16x16x32_bf16 v[20:23], v[144:147], v[236:239], v[20:23]
	v_mfma_f32_16x16x32_bf16 v[120:123], v[140:143], v[216:219], v[120:123]
	v_mfma_f32_16x16x32_bf16 v[116:119], v[170:173], v[216:219], v[116:119]
	v_mfma_f32_16x16x32_bf16 v[96:99], v[140:143], v[224:227], v[96:99]
	v_mfma_f32_16x16x32_bf16 v[92:95], v[170:173], v[224:227], v[92:95]
	v_mfma_f32_16x16x32_bf16 v[64:67], v[140:143], v[232:235], v[64:67]
	v_mfma_f32_16x16x32_bf16 v[60:63], v[170:173], v[232:235], v[60:63]
	v_mfma_f32_16x16x32_bf16 v[24:27], v[140:143], v[240:243], v[24:27]
	v_mfma_f32_16x16x32_bf16 v[20:23], v[170:173], v[240:243], v[20:23]
	s_setprio 0
	s_setprio 1
	v_mfma_f32_16x16x32_bf16 v[112:115], v[174:177], v[212:215], v[112:115]
	v_mfma_f32_16x16x32_bf16 v[108:111], v[182:185], v[212:215], v[108:111]
	v_mfma_f32_16x16x32_bf16 v[88:91], v[174:177], v[220:223], v[88:91]
	v_mfma_f32_16x16x32_bf16 v[84:87], v[182:185], v[220:223], v[84:87]
	v_mfma_f32_16x16x32_bf16 v[48:51], v[174:177], v[228:231], v[48:51]
	v_mfma_f32_16x16x32_bf16 v[44:47], v[182:185], v[228:231], v[44:47]
	v_mfma_f32_16x16x32_bf16 v[16:19], v[174:177], v[236:239], v[16:19]
	v_mfma_f32_16x16x32_bf16 v[12:15], v[182:185], v[236:239], v[12:15]
	v_mfma_f32_16x16x32_bf16 v[112:115], v[178:181], v[216:219], v[112:115]
	v_mfma_f32_16x16x32_bf16 v[108:111], v[208:211], v[216:219], v[108:111]
	v_mfma_f32_16x16x32_bf16 v[88:91], v[178:181], v[224:227], v[88:91]
	v_mfma_f32_16x16x32_bf16 v[84:87], v[208:211], v[224:227], v[84:87]
	s_setprio 2
	s_barrier
	v_mfma_f32_16x16x32_bf16 v[48:51], v[178:181], v[232:235], v[48:51]
	v_mfma_f32_16x16x32_bf16 v[44:47], v[208:211], v[232:235], v[44:47]
	v_mfma_f32_16x16x32_bf16 v[16:19], v[178:181], v[240:243], v[16:19]
	v_mfma_f32_16x16x32_bf16 v[12:15], v[208:211], v[240:243], v[12:15]
	s_setprio 0
	s_add_i32 s24, s24, 2
	s_cmp_gt_u32 s24, 29
	s_mov_b64 s[10:11], vcc
	s_cbranch_scc0 .LBB0_667
	s_and_b64 vcc, exec, s[44:45]
	s_cbranch_vccz .LBB0_670
	s_barrier

; #define PG8_STAGE(bufoff, gbase, voff) do { _Pragma("unroll") for (int _i = 0; _i < 2; ++_i) \
;         __builtin_amdgcn_global_load_lds((const unsigned*)((const char*)(gbase) + (voff)[_i]), (LAS unsigned*)(lds + (bufoff) + ldsw + _i * 8192), 16, 0, 0); } while (0)
; #define PG8_LDA(dst, b, h) do { _Pragma("unroll") for (int m = 0; m < 4; ++m) _Pragma("unroll") for (int k = 0; k < 2; ++k) dst[m][k] = *(const LAS bf16x8*)(lds + PG8_SA(b, h) + aoff + m * 2048 + k * 1024); } while (0)
; #define PG8_LDB(dst, b, h) do { _Pragma("unroll") for (int n = 0; n < 2; ++n) _Pragma("unroll") for (int k = 0; k < 2; ++k) dst[n][k] = *(const LAS bf16x8*)(lds + PG8_SB(b, h) + boff + n * 2048 + k * 1024); } while (0)
; #define PG8_MMA(ai, bj, At, Bt) do { __builtin_amdgcn_s_setprio(1); _Pragma("unroll") for (int m = 0; m < 4; ++m) _Pragma("unroll") for (int n = 0; n < 2; ++n) _Pragma("unroll") for (int k = 0; k < 2; ++k) \
;         acc[ai][bj][m][n] = __builtin_amdgcn_mfma_f32_16x16x32_bf16(Bt[n][k], At[m][k], acc[ai][bj][m][n], 0, 0, 0); __builtin_amdgcn_s_setprio(0); } while (0)
; #define PG8_WAIT_V(n) asm volatile("s_waitcnt vmcnt(" #n ")" ::: "memory")
; #define PG8_WAIT_L(n) asm volatile("s_waitcnt lgkmcnt(" #n ")" ::: "memory")
; #define PG8_BAR __builtin_amdgcn_s_barrier()
; #define PG8_SCHED __builtin_amdgcn_sched_barrier(0)
; template <class Epi, class Sched, bool ALIGN_EPI = true>
; __device__ __forceinline__ void gemm_phase(LAS unsigned char* lds, const Gemm g, const Sched& S, const Epi& E) {
;     ...
;             PG8_LDB(B0, 0, 0); PG8_LDB(B1, 0, 1); PG8_SCHED; PG8_LDA(At, 0, 0); PG8_STAGE(PG8_SA(1, 1), a1 + hA, voffA);
;             PG8_WAIT_V(8); PG8_WAIT_L(0); PG8_BAR; PG8_MMA(0, 0, At, B0); PG8_MMA(0, 1, At, B1); PG8_BAR; PG8_SCHED;
;             PG8_LDA(At, 0, 1); PG8_STAGE(PG8_SB(0, 0), b2, voffB); PG8_STAGE(PG8_SB(0, 1), b2 + hB, voffB); PG8_STAGE(PG8_SA(0, 0), a2, voffA);
;             PG8_WAIT_V(8); PG8_WAIT_L(0); PG8_BAR; PG8_MMA(1, 0, At, B0); PG8_MMA(1, 1, At, B1); PG8_BAR; PG8_SCHED;
.LBB0_828:
	s_add_u32 s26, s6, 0xfff80080
	s_addc_u32 s27, s7, -1
	s_add_i32 s30, 0, 0x10000
	s_cmp_eq_u32 s25, 28
	s_cselect_b32 s59, s16, s27
	s_cselect_b32 s58, s17, s26
	v_add_u32_e32 v2, s30, v204
	s_cselect_b32 s45, s15, s24
	s_cselect_b32 s44, s18, s19
	s_add_i32 s31, 0, 0x14000
	ds_read_b128 v[132:135], v2
	ds_read_b128 v[136:139], v2 offset:1024
	ds_read_b128 v[140:143], v2 offset:2048
	ds_read_b128 v[144:147], v2 offset:3072
	v_add_u32_e32 v2, s31, v204
	ds_read_b128 v[148:151], v2
	ds_read_b128 v[152:155], v2 offset:1024
	ds_read_b128 v[174:177], v2 offset:2048
	ds_read_b128 v[178:181], v2 offset:3072
	v_lshl_add_u64 v[156:157], s[6:7], 0, v[170:171]
	s_add_i32 m0, s62, 0xc000
	ds_read_b128 v[182:185], v205
	ds_read_b128 v[186:189], v205 offset:1024
	ds_read_b128 v[190:193], v205 offset:2048
	ds_read_b128 v[194:197], v205 offset:3072
	ds_read_b128 v[206:209], v205 offset:4096
	ds_read_b128 v[210:213], v205 offset:5120
	ds_read_b128 v[214:217], v205 offset:6144
	ds_read_b128 v[218:221], v205 offset:7168
	global_load_lds_dwordx4 v[156:157], off
	v_lshl_add_u64 v[156:157], s[6:7], 0, v[172:173]
	s_add_i32 m0, s62, 0xe000
	s_nop 0
	global_load_lds_dwordx4 v[156:157], off
	s_waitcnt vmcnt(8)
	s_cmp_lg_u64 s[12:13], 0
	s_cbranch_scc1 .Llgk_828_0
	s_waitcnt lgkmcnt(0)
.Llgk_828_0:
	s_barrier
	s_setprio 1
	s_waitcnt lgkmcnt(0)
	v_mfma_f32_16x16x32_bf16 v[116:119], v[132:135], v[182:185], v[116:119]
	v_mfma_f32_16x16x32_bf16 v[100:103], v[140:143], v[182:185], v[100:103]
	v_mfma_f32_16x16x32_bf16 v[108:111], v[132:135], v[190:193], v[108:111]
	v_mfma_f32_16x16x32_bf16 v[96:99], v[140:143], v[190:193], v[96:99]
	v_mfma_f32_16x16x32_bf16 v[88:91], v[132:135], v[206:209], v[88:91]
	v_mfma_f32_16x16x32_bf16 v[84:87], v[140:143], v[206:209], v[84:87]
	v_mfma_f32_16x16x32_bf16 v[72:75], v[132:135], v[214:217], v[72:75]
	v_mfma_f32_16x16x32_bf16 v[80:83], v[140:143], v[214:217], v[80:83]
	v_mfma_f32_16x16x32_bf16 v[116:119], v[136:139], v[186:189], v[116:119]
	v_mfma_f32_16x16x32_bf16 v[100:103], v[144:147], v[186:189], v[100:103]
	v_mfma_f32_16x16x32_bf16 v[108:111], v[136:139], v[194:197], v[108:111]
	v_mfma_f32_16x16x32_bf16 v[96:99], v[144:147], v[194:197], v[96:99]
	v_mfma_f32_16x16x32_bf16 v[88:91], v[136:139], v[210:213], v[88:91]
	v_mfma_f32_16x16x32_bf16 v[84:87], v[144:147], v[210:213], v[84:87]
	v_mfma_f32_16x16x32_bf16 v[72:75], v[136:139], v[218:221], v[72:75]
	v_mfma_f32_16x16x32_bf16 v[80:83], v[144:147], v[218:221], v[80:83]
	s_setprio 0
	s_setprio 1
	v_mfma_f32_16x16x32_bf16 v[128:131], v[148:151], v[182:185], v[128:131]
	v_mfma_f32_16x16x32_bf16 v[44:47], v[174:177], v[182:185], v[44:47]
	v_mfma_f32_16x16x32_bf16 v[124:127], v[148:151], v[190:193], v[124:127]
	v_mfma_f32_16x16x32_bf16 v[36:39], v[174:177], v[190:193], v[36:39]
	v_mfma_f32_16x16x32_bf16 v[120:123], v[148:151], v[206:209], v[120:123]
	v_mfma_f32_16x16x32_bf16 v[32:35], v[174:177], v[206:209], v[32:35]
	v_mfma_f32_16x16x32_bf16 v[112:115], v[148:151], v[214:217], v[112:115]
	v_mfma_f32_16x16x32_bf16 v[28:31], v[174:177], v[214:217], v[28:31]
	v_mfma_f32_16x16x32_bf16 v[128:131], v[152:155], v[186:189], v[128:131]
	v_mfma_f32_16x16x32_bf16 v[44:47], v[178:181], v[186:189], v[44:47]
	v_mfma_f32_16x16x32_bf16 v[124:127], v[152:155], v[194:197], v[124:127]
	v_mfma_f32_16x16x32_bf16 v[36:39], v[178:181], v[194:197], v[36:39]
	s_setprio 2
	s_barrier
	v_mfma_f32_16x16x32_bf16 v[120:123], v[152:155], v[210:213], v[120:123]
	v_mfma_f32_16x16x32_bf16 v[32:35], v[178:181], v[210:213], v[32:35]
	v_mfma_f32_16x16x32_bf16 v[112:115], v[152:155], v[218:221], v[112:115]
	v_mfma_f32_16x16x32_bf16 v[28:31], v[178:181], v[218:221], v[28:31]
	s_setprio 0
	s_add_i32 s26, s30, s61
	v_lshl_add_u64 v[156:157], s[44:45], 0, v[166:167]
	s_mov_b32 m0, s26
	ds_read_b128 v[182:185], v205 offset:16384
	ds_read_b128 v[186:189], v205 offset:17408
	ds_read_b128 v[190:193], v205 offset:18432
	ds_read_b128 v[194:197], v205 offset:19456
	ds_read_b128 v[206:209], v205 offset:20480
	ds_read_b128 v[210:213], v205 offset:21504
	ds_read_b128 v[214:217], v205 offset:22528
	ds_read_b128 v[218:221], v205 offset:23552
	global_load_lds_dwordx4 v[156:157], off
	s_add_i32 m0, s26, 0x2000
	s_add_u32 s26, s44, 0x80000
	v_lshl_add_u64 v[160:161], s[44:45], 0, v[0:1]
	s_addc_u32 s27, s45, 0
	s_add_i32 s30, s31, s61
	global_load_lds_dwordx4 v[160:161], off
	v_lshl_add_u64 v[162:163], s[26:27], 0, v[166:167]
	s_mov_b32 m0, s30
	v_lshl_add_u64 v[222:223], s[58:59], 0, v[164:165]
	global_load_lds_dwordx4 v[162:163], off
	v_lshl_add_u64 v[162:163], s[26:27], 0, v[0:1]
	s_add_i32 m0, s30, 0x2000
	s_nop 0
	global_load_lds_dwordx4 v[162:163], off
	v_lshl_add_u64 v[162:163], s[58:59], 0, v[168:169]
	s_mov_b32 m0, s62
	s_nop 0
	global_load_lds_dwordx4 v[162:163], off
	s_mov_b32 m0, s63
	s_nop 0
	global_load_lds_dwordx4 v[222:223], off
	s_waitcnt vmcnt(8)
	s_cmp_lg_u64 s[12:13], 0
	s_cbranch_scc1 .Llgk_828_1
	s_waitcnt lgkmcnt(0)
; #define PG8_STAGE(bufoff, gbase, voff) do { _Pragma("unroll") for (int _i = 0; _i < 2; ++_i) \
;         __builtin_amdgcn_global_load_lds((const unsigned*)((const char*)(gbase) + (voff)[_i]), (LAS unsigned*)(lds + (bufoff) + ldsw + _i * 8192), 16, 0, 0); } while (0)
; #define PG8_LDA(dst, b, h) do { _Pragma("unroll") for (int m = 0; m < 4; ++m) _Pragma("unroll") for (int k = 0; k < 2; ++k) dst[m][k] = *(const LAS bf16x8*)(lds + PG8_SA(b, h) + aoff + m * 2048 + k * 1024); } while (0)
; #define PG8_LDB(dst, b, h) do { _Pragma("unroll") for (int n = 0; n < 2; ++n) _Pragma("unroll") for (int k = 0; k < 2; ++k) dst[n][k] = *(const LAS bf16x8*)(lds + PG8_SB(b, h) + boff + n * 2048 + k * 1024); } while (0)
; #define PG8_MMA(ai, bj, At, Bt) do { __builtin_amdgcn_s_setprio(1); _Pragma("unroll") for (int m = 0; m < 4; ++m) _Pragma("unroll") for (int n = 0; n < 2; ++n) _Pragma("unroll") for (int k = 0; k < 2; ++k) \
;         acc[ai][bj][m][n] = __builtin_amdgcn_mfma_f32_16x16x32_bf16(Bt[n][k], At[m][k], acc[ai][bj][m][n], 0, 0, 0); __builtin_amdgcn_s_setprio(0); } while (0)
; #define PG8_WAIT_V(n) asm volatile("s_waitcnt vmcnt(" #n ")" ::: "memory")
; #define PG8_WAIT_L(n) asm volatile("s_waitcnt lgkmcnt(" #n ")" ::: "memory")
; #define PG8_BAR __builtin_amdgcn_s_barrier()
; #define PG8_SCHED __builtin_amdgcn_sched_barrier(0)
; template <class Epi, class Sched, bool ALIGN_EPI = true>
; __device__ __forceinline__ void gemm_phase(LAS unsigned char* lds, const Gemm g, const Sched& S, const Epi& E) {
;     ...
;             PG8_WAIT_V(8); PG8_WAIT_L(0); PG8_BAR; PG8_MMA(1, 0, At, B0); PG8_MMA(1, 1, At, B1); PG8_BAR; PG8_SCHED;
;             PG8_LDB(B0, 1, 0); PG8_LDB(B1, 1, 1); PG8_SCHED; PG8_LDA(At, 1, 0); PG8_STAGE(PG8_SA(0, 1), a2 + hA, voffA);
;             PG8_WAIT_V(8); PG8_WAIT_L(0); PG8_BAR; PG8_MMA(0, 0, At, B0); PG8_MMA(0, 1, At, B1); PG8_BAR; PG8_SCHED;
.Llgk_828_1:
	s_barrier
	s_setprio 1
	s_waitcnt lgkmcnt(0)
	v_mfma_f32_16x16x32_bf16 v[60:63], v[132:135], v[182:185], v[60:63]
	v_mfma_f32_16x16x32_bf16 v[68:71], v[140:143], v[182:185], v[68:71]
	v_mfma_f32_16x16x32_bf16 v[40:43], v[132:135], v[190:193], v[40:43]
	v_mfma_f32_16x16x32_bf16 v[64:67], v[140:143], v[190:193], v[64:67]
	v_mfma_f32_16x16x32_bf16 v[24:27], v[132:135], v[206:209], v[24:27]
	v_mfma_f32_16x16x32_bf16 v[56:59], v[140:143], v[206:209], v[56:59]
	v_mfma_f32_16x16x32_bf16 v[12:15], v[132:135], v[214:217], v[12:15]
	v_mfma_f32_16x16x32_bf16 v[48:51], v[140:143], v[214:217], v[48:51]
	v_mfma_f32_16x16x32_bf16 v[60:63], v[136:139], v[186:189], v[60:63]
	v_mfma_f32_16x16x32_bf16 v[68:71], v[144:147], v[186:189], v[68:71]
	v_mfma_f32_16x16x32_bf16 v[40:43], v[136:139], v[194:197], v[40:43]
	v_mfma_f32_16x16x32_bf16 v[64:67], v[144:147], v[194:197], v[64:67]
	v_mfma_f32_16x16x32_bf16 v[24:27], v[136:139], v[210:213], v[24:27]
	v_mfma_f32_16x16x32_bf16 v[56:59], v[144:147], v[210:213], v[56:59]
	v_mfma_f32_16x16x32_bf16 v[12:15], v[136:139], v[218:221], v[12:15]
	v_mfma_f32_16x16x32_bf16 v[48:51], v[144:147], v[218:221], v[48:51]
	s_setprio 0
	s_setprio 1
	v_mfma_f32_16x16x32_bf16 v[104:107], v[148:151], v[182:185], v[104:107]
	v_mfma_f32_16x16x32_bf16 v[20:23], v[174:177], v[182:185], v[20:23]
	v_mfma_f32_16x16x32_bf16 v[92:95], v[148:151], v[190:193], v[92:95]
	v_mfma_f32_16x16x32_bf16 v[16:19], v[174:177], v[190:193], v[16:19]
	v_mfma_f32_16x16x32_bf16 v[76:79], v[148:151], v[206:209], v[76:79]
	v_mfma_f32_16x16x32_bf16 v[8:11], v[174:177], v[206:209], v[8:11]
	v_mfma_f32_16x16x32_bf16 v[52:55], v[148:151], v[214:217], v[52:55]
	v_mfma_f32_16x16x32_bf16 v[4:7], v[174:177], v[214:217], v[4:7]
	v_mfma_f32_16x16x32_bf16 v[104:107], v[152:155], v[186:189], v[104:107]
	v_mfma_f32_16x16x32_bf16 v[20:23], v[178:181], v[186:189], v[20:23]
	v_mfma_f32_16x16x32_bf16 v[92:95], v[152:155], v[194:197], v[92:95]
	v_mfma_f32_16x16x32_bf16 v[16:19], v[178:181], v[194:197], v[16:19]
	s_setprio 2
	s_barrier
	v_mfma_f32_16x16x32_bf16 v[76:79], v[152:155], v[210:213], v[76:79]
	v_mfma_f32_16x16x32_bf16 v[8:11], v[178:181], v[210:213], v[8:11]
	v_mfma_f32_16x16x32_bf16 v[52:55], v[152:155], v[218:221], v[52:55]
	v_mfma_f32_16x16x32_bf16 v[4:7], v[178:181], v[218:221], v[4:7]
	s_setprio 0
	s_add_i32 s30, 0, 0x18000
	v_add_u32_e32 v2, s30, v204
	s_add_i32 s31, 0, 0x1c000
	ds_read_b128 v[132:135], v2
	ds_read_b128 v[136:139], v2 offset:1024
	ds_read_b128 v[140:143], v2 offset:2048
	ds_read_b128 v[144:147], v2 offset:3072
	v_add_u32_e32 v2, s31, v204
	ds_read_b128 v[148:151], v2
	ds_read_b128 v[152:155], v2 offset:1024
	ds_read_b128 v[174:177], v2 offset:2048
	ds_read_b128 v[178:181], v2 offset:3072
	s_add_u32 s26, s58, 0x80000
	s_addc_u32 s27, s59, 0
	s_mov_b32 m0, s64
	v_lshl_add_u64 v[224:225], s[26:27], 0, v[168:169]
	ds_read_b128 v[182:185], v205 offset:32768
	ds_read_b128 v[186:189], v205 offset:33792
	ds_read_b128 v[190:193], v205 offset:34816
	ds_read_b128 v[194:197], v205 offset:35840
	ds_read_b128 v[206:209], v205 offset:36864
	ds_read_b128 v[210:213], v205 offset:37888
	ds_read_b128 v[214:217], v205 offset:38912
	ds_read_b128 v[218:221], v205 offset:39936
	global_load_lds_dwordx4 v[224:225], off
	v_lshl_add_u64 v[224:225], s[26:27], 0, v[164:165]
	s_mov_b32 m0, s65
	s_nop 0
	global_load_lds_dwordx4 v[224:225], off
	s_waitcnt vmcnt(8)
	s_cmp_lg_u64 s[12:13], 0
	s_cbranch_scc1 .Llgk_828_2
	s_waitcnt lgkmcnt(0)
; #define PG8_STAGE(bufoff, gbase, voff) do { _Pragma("unroll") for (int _i = 0; _i < 2; ++_i) \
;         __builtin_amdgcn_global_load_lds((const unsigned*)((const char*)(gbase) + (voff)[_i]), (LAS unsigned*)(lds + (bufoff) + ldsw + _i * 8192), 16, 0, 0); } while (0)
; #define PG8_LDA(dst, b, h) do { _Pragma("unroll") for (int m = 0; m < 4; ++m) _Pragma("unroll") for (int k = 0; k < 2; ++k) dst[m][k] = *(const LAS bf16x8*)(lds + PG8_SA(b, h) + aoff + m * 2048 + k * 1024); } while (0)
; #define PG8_MMA(ai, bj, At, Bt) do { __builtin_amdgcn_s_setprio(1); _Pragma("unroll") for (int m = 0; m < 4; ++m) _Pragma("unroll") for (int n = 0; n < 2; ++n) _Pragma("unroll") for (int k = 0; k < 2; ++k) \
;         acc[ai][bj][m][n] = __builtin_amdgcn_mfma_f32_16x16x32_bf16(Bt[n][k], At[m][k], acc[ai][bj][m][n], 0, 0, 0); __builtin_amdgcn_s_setprio(0); } while (0)
; #define PG8_WAIT_V(n) asm volatile("s_waitcnt vmcnt(" #n ")" ::: "memory")
; #define PG8_WAIT_L(n) asm volatile("s_waitcnt lgkmcnt(" #n ")" ::: "memory")
; #define PG8_BAR __builtin_amdgcn_s_barrier()
; #define PG8_SCHED __builtin_amdgcn_sched_barrier(0)
; template <class Epi, class Sched, bool ALIGN_EPI = true>
; __device__ __forceinline__ void gemm_phase(LAS unsigned char* lds, const Gemm g, const Sched& S, const Epi& E) {
;     ...
;             PG8_WAIT_V(8); PG8_WAIT_L(0); PG8_BAR; PG8_MMA(0, 0, At, B0); PG8_MMA(0, 1, At, B1); PG8_BAR; PG8_SCHED;
;             PG8_LDA(At, 1, 1); PG8_STAGE(PG8_SB(1, 0), b3, voffB); PG8_STAGE(PG8_SB(1, 1), b3 + hB, voffB); PG8_STAGE(PG8_SA(1, 0), a3, voffA);
;             PG8_WAIT_V(8); PG8_WAIT_L(0); PG8_BAR; PG8_MMA(1, 0, At, B0); PG8_MMA(1, 1, At, B1); PG8_BAR; PG8_SCHED;
;         }
;         if constexpr (ALIGN_EPI) { if (wr == 0) PG8_BAR; }
.Llgk_828_2:
	s_barrier
	s_setprio 1
	s_waitcnt lgkmcnt(0)
	v_mfma_f32_16x16x32_bf16 v[116:119], v[132:135], v[182:185], v[116:119]
	v_mfma_f32_16x16x32_bf16 v[100:103], v[140:143], v[182:185], v[100:103]
	v_mfma_f32_16x16x32_bf16 v[108:111], v[132:135], v[190:193], v[108:111]
	v_mfma_f32_16x16x32_bf16 v[96:99], v[140:143], v[190:193], v[96:99]
	v_mfma_f32_16x16x32_bf16 v[88:91], v[132:135], v[206:209], v[88:91]
	v_mfma_f32_16x16x32_bf16 v[84:87], v[140:143], v[206:209], v[84:87]
	v_mfma_f32_16x16x32_bf16 v[72:75], v[132:135], v[214:217], v[72:75]
	v_mfma_f32_16x16x32_bf16 v[80:83], v[140:143], v[214:217], v[80:83]
	v_mfma_f32_16x16x32_bf16 v[116:119], v[136:139], v[186:189], v[116:119]
	v_mfma_f32_16x16x32_bf16 v[100:103], v[144:147], v[186:189], v[100:103]
	v_mfma_f32_16x16x32_bf16 v[108:111], v[136:139], v[194:197], v[108:111]
	v_mfma_f32_16x16x32_bf16 v[96:99], v[144:147], v[194:197], v[96:99]
	v_mfma_f32_16x16x32_bf16 v[88:91], v[136:139], v[210:213], v[88:91]
	v_mfma_f32_16x16x32_bf16 v[84:87], v[144:147], v[210:213], v[84:87]
	v_mfma_f32_16x16x32_bf16 v[72:75], v[136:139], v[218:221], v[72:75]
	v_mfma_f32_16x16x32_bf16 v[80:83], v[144:147], v[218:221], v[80:83]
	s_setprio 0
	s_setprio 1
	v_mfma_f32_16x16x32_bf16 v[128:131], v[148:151], v[182:185], v[128:131]
	v_mfma_f32_16x16x32_bf16 v[44:47], v[174:177], v[182:185], v[44:47]
	v_mfma_f32_16x16x32_bf16 v[124:127], v[148:151], v[190:193], v[124:127]
	v_mfma_f32_16x16x32_bf16 v[36:39], v[174:177], v[190:193], v[36:39]
	v_mfma_f32_16x16x32_bf16 v[120:123], v[148:151], v[206:209], v[120:123]
	v_mfma_f32_16x16x32_bf16 v[32:35], v[174:177], v[206:209], v[32:35]
	v_mfma_f32_16x16x32_bf16 v[112:115], v[148:151], v[214:217], v[112:115]
	v_mfma_f32_16x16x32_bf16 v[28:31], v[174:177], v[214:217], v[28:31]
	v_mfma_f32_16x16x32_bf16 v[128:131], v[152:155], v[186:189], v[128:131]
	v_mfma_f32_16x16x32_bf16 v[44:47], v[178:181], v[186:189], v[44:47]
	v_mfma_f32_16x16x32_bf16 v[124:127], v[152:155], v[194:197], v[124:127]
	v_mfma_f32_16x16x32_bf16 v[36:39], v[178:181], v[194:197], v[36:39]
	s_setprio 2
	s_barrier
	v_mfma_f32_16x16x32_bf16 v[120:123], v[152:155], v[210:213], v[120:123]
	v_mfma_f32_16x16x32_bf16 v[32:35], v[178:181], v[210:213], v[32:35]
	v_mfma_f32_16x16x32_bf16 v[112:115], v[152:155], v[218:221], v[112:115]
	v_mfma_f32_16x16x32_bf16 v[28:31], v[178:181], v[218:221], v[28:31]
	s_setprio 0
	s_add_i32 s26, s30, s61
	v_lshl_add_u64 v[156:157], v[156:157], 0, s[86:87]
	s_mov_b32 m0, s26
	ds_read_b128 v[182:185], v205 offset:49152
	ds_read_b128 v[186:189], v205 offset:50176
	ds_read_b128 v[190:193], v205 offset:51200
	ds_read_b128 v[194:197], v205 offset:52224
	ds_read_b128 v[206:209], v205 offset:53248
	ds_read_b128 v[210:213], v205 offset:54272
	ds_read_b128 v[214:217], v205 offset:55296
	ds_read_b128 v[218:221], v205 offset:56320
	global_load_lds_dwordx4 v[156:157], off
	s_add_i32 m0, s26, 0x2000
	s_add_u32 s26, s44, 0x80080
	v_lshl_add_u64 v[156:157], v[160:161], 0, s[86:87]
	s_addc_u32 s27, s45, 0
	s_add_i32 s30, s31, s61
	global_load_lds_dwordx4 v[156:157], off
	v_lshl_add_u64 v[156:157], s[26:27], 0, v[166:167]
	s_mov_b32 m0, s30
	s_nop 0
	global_load_lds_dwordx4 v[156:157], off
	v_lshl_add_u64 v[156:157], s[26:27], 0, v[0:1]
	s_add_i32 m0, s30, 0x2000
	s_nop 0
	global_load_lds_dwordx4 v[156:157], off
	v_lshl_add_u64 v[156:157], v[162:163], 0, s[86:87]
	s_mov_b32 m0, s75
	s_nop 0
	global_load_lds_dwordx4 v[156:157], off
	v_lshl_add_u64 v[156:157], v[222:223], 0, s[86:87]
	s_mov_b32 m0, s76
	s_nop 0
	global_load_lds_dwordx4 v[156:157], off
	s_waitcnt vmcnt(8)
	s_cmp_lg_u64 s[12:13], 0
	s_cbranch_scc1 .Llgk_828_3
	s_waitcnt lgkmcnt(0)
.Llgk_828_3:
	s_barrier
	s_setprio 1
	s_waitcnt lgkmcnt(0)
	v_mfma_f32_16x16x32_bf16 v[60:63], v[132:135], v[182:185], v[60:63]
	v_mfma_f32_16x16x32_bf16 v[68:71], v[140:143], v[182:185], v[68:71]
	v_mfma_f32_16x16x32_bf16 v[40:43], v[132:135], v[190:193], v[40:43]
	v_mfma_f32_16x16x32_bf16 v[64:67], v[140:143], v[190:193], v[64:67]
	v_mfma_f32_16x16x32_bf16 v[24:27], v[132:135], v[206:209], v[24:27]
	v_mfma_f32_16x16x32_bf16 v[56:59], v[140:143], v[206:209], v[56:59]
	v_mfma_f32_16x16x32_bf16 v[12:15], v[132:135], v[214:217], v[12:15]
	v_mfma_f32_16x16x32_bf16 v[48:51], v[140:143], v[214:217], v[48:51]
	v_mfma_f32_16x16x32_bf16 v[60:63], v[136:139], v[186:189], v[60:63]
	v_mfma_f32_16x16x32_bf16 v[68:71], v[144:147], v[186:189], v[68:71]
	v_mfma_f32_16x16x32_bf16 v[40:43], v[136:139], v[194:197], v[40:43]
	v_mfma_f32_16x16x32_bf16 v[64:67], v[144:147], v[194:197], v[64:67]
	v_mfma_f32_16x16x32_bf16 v[24:27], v[136:139], v[210:213], v[24:27]
	v_mfma_f32_16x16x32_bf16 v[56:59], v[144:147], v[210:213], v[56:59]
	v_mfma_f32_16x16x32_bf16 v[12:15], v[136:139], v[218:221], v[12:15]
	v_mfma_f32_16x16x32_bf16 v[48:51], v[144:147], v[218:221], v[48:51]
	s_setprio 0
	s_setprio 1
	v_mfma_f32_16x16x32_bf16 v[104:107], v[148:151], v[182:185], v[104:107]
	v_mfma_f32_16x16x32_bf16 v[20:23], v[174:177], v[182:185], v[20:23]
	v_mfma_f32_16x16x32_bf16 v[92:95], v[148:151], v[190:193], v[92:95]
	v_mfma_f32_16x16x32_bf16 v[16:19], v[174:177], v[190:193], v[16:19]
	v_mfma_f32_16x16x32_bf16 v[76:79], v[148:151], v[206:209], v[76:79]
	v_mfma_f32_16x16x32_bf16 v[8:11], v[174:177], v[206:209], v[8:11]
	v_mfma_f32_16x16x32_bf16 v[52:55], v[148:151], v[214:217], v[52:55]
	v_mfma_f32_16x16x32_bf16 v[4:7], v[174:177], v[214:217], v[4:7]
	v_mfma_f32_16x16x32_bf16 v[104:107], v[152:155], v[186:189], v[104:107]
	v_mfma_f32_16x16x32_bf16 v[20:23], v[178:181], v[186:189], v[20:23]
	v_mfma_f32_16x16x32_bf16 v[92:95], v[152:155], v[194:197], v[92:95]
	v_mfma_f32_16x16x32_bf16 v[16:19], v[178:181], v[194:197], v[16:19]
	s_setprio 2
	s_barrier
	v_mfma_f32_16x16x32_bf16 v[76:79], v[152:155], v[210:213], v[76:79]
	v_mfma_f32_16x16x32_bf16 v[8:11], v[178:181], v[210:213], v[8:11]
	v_mfma_f32_16x16x32_bf16 v[52:55], v[152:155], v[218:221], v[52:55]
	v_mfma_f32_16x16x32_bf16 v[4:7], v[178:181], v[218:221], v[4:7]
	s_setprio 0
	s_add_i32 s25, s25, 2
	s_add_u32 s6, s6, 0x100
	s_addc_u32 s7, s7, 0
	s_add_u32 s19, s19, 0x100
	s_addc_u32 s24, s24, 0
	s_cmp_gt_u32 s25, 29
	s_cbranch_scc0 .LBB0_828
	s_and_b64 vcc, exec, s[12:13]
	s_cbranch_vccz .LBB0_831
	s_barrier

; #define PG8_STAGE(bufoff, gbase, voff) do { _Pragma("unroll") for (int _i = 0; _i < 2; ++_i) \
;         __builtin_amdgcn_global_load_lds((const unsigned*)((const char*)(gbase) + (voff)[_i]), (LAS unsigned*)(lds + (bufoff) + ldsw + _i * 8192), 16, 0, 0); } while (0)
; #define PG8_LDA(dst, b, h) do { _Pragma("unroll") for (int m = 0; m < 4; ++m) _Pragma("unroll") for (int k = 0; k < 2; ++k) dst[m][k] = *(const LAS bf16x8*)(lds + PG8_SA(b, h) + aoff + m * 2048 + k * 1024); } while (0)
; #define PG8_LDB(dst, b, h) do { _Pragma("unroll") for (int n = 0; n < 2; ++n) _Pragma("unroll") for (int k = 0; k < 2; ++k) dst[n][k] = *(const LAS bf16x8*)(lds + PG8_SB(b, h) + boff + n * 2048 + k * 1024); } while (0)
; #define PG8_MMA(ai, bj, At, Bt) do { __builtin_amdgcn_s_setprio(1); _Pragma("unroll") for (int m = 0; m < 4; ++m) _Pragma("unroll") for (int n = 0; n < 2; ++n) _Pragma("unroll") for (int k = 0; k < 2; ++k) \
;         acc[ai][bj][m][n] = __builtin_amdgcn_mfma_f32_16x16x32_bf16(Bt[n][k], At[m][k], acc[ai][bj][m][n], 0, 0, 0); __builtin_amdgcn_s_setprio(0); } while (0)
; #define PG8_WAIT_V(n) asm volatile("s_waitcnt vmcnt(" #n ")" ::: "memory")
; #define PG8_WAIT_L(n) asm volatile("s_waitcnt lgkmcnt(" #n ")" ::: "memory")
; #define PG8_BAR __builtin_amdgcn_s_barrier()
; #define PG8_SCHED __builtin_amdgcn_sched_barrier(0)
; template <class Epi, class Sched, bool ALIGN_EPI = true>
; __device__ __forceinline__ void gemm_phase(LAS unsigned char* lds, const Gemm g, const Sched& S, const Epi& E) {
;     ...
;             const bool last = (t == nt - 2);
;             const char* a1 = cA + (size_t)(t + 1) * kstep;
;             const char* a2 = last ? nA : cA + (size_t)(t + 2) * kstep; const char* b2 = last ? nB : cB + (size_t)(t + 2) * kstep;
;             const char* a3 = a2 + kstep; const char* b3 = b2 + kstep;
;             PG8_LDB(B0, 0, 0); PG8_LDB(B1, 0, 1); PG8_SCHED; PG8_LDA(At, 0, 0); PG8_STAGE(PG8_SA(1, 1), a1 + hA, voffA);
;             PG8_WAIT_V(8); PG8_WAIT_L(0); PG8_BAR; PG8_MMA(0, 0, At, B0); PG8_MMA(0, 1, At, B1); PG8_BAR; PG8_SCHED;
;             PG8_LDA(At, 0, 1); PG8_STAGE(PG8_SB(0, 0), b2, voffB); PG8_STAGE(PG8_SB(0, 1), b2 + hB, voffB); PG8_STAGE(PG8_SA(0, 0), a2, voffA);
;             PG8_WAIT_V(8); PG8_WAIT_L(0); PG8_BAR; PG8_MMA(1, 0, At, B0); PG8_MMA(1, 1, At, B1); PG8_BAR; PG8_SCHED;
.LBB0_1111:
	s_add_u32 vcc_lo, s10, 0x100
	s_addc_u32 vcc_hi, s11, 0
	s_add_u32 s19, s16, s10
	s_addc_u32 s24, s17, s11
	s_add_i32 s25, 0, 0x10000
	s_cmpk_eq_i32 s18, 0x54
	s_cselect_b32 s65, s61, s24
	s_cselect_b32 s24, 0, vcc_lo
	s_cselect_b32 s64, s60, s19
	s_cselect_b32 s19, 0, vcc_hi
	s_add_u32 s62, s2, s24
	v_add_u32_e32 v160, s25, v188
	s_addc_u32 s63, s3, s19
	s_add_i32 s19, 0, 0x14000
	ds_read_b128 v[136:139], v160
	ds_read_b128 v[140:143], v160 offset:1024
	ds_read_b128 v[144:147], v160 offset:2048
	ds_read_b128 v[172:175], v160 offset:3072
	v_add_u32_e32 v160, s19, v188
	ds_read_b128 v[176:179], v160
	ds_read_b128 v[180:183], v160 offset:1024
	ds_read_b128 v[184:187], v160 offset:2048
	ds_read_b128 v[208:211], v160 offset:3072
	v_lshl_add_u64 v[160:161], v[132:133], 0, s[10:11]
	s_add_i32 m0, s67, 0xc000
	ds_read_b128 v[212:215], v197
	ds_read_b128 v[216:219], v197 offset:1024
	ds_read_b128 v[220:223], v197 offset:2048
	ds_read_b128 v[224:227], v197 offset:3072
	ds_read_b128 v[228:231], v197 offset:4096
	ds_read_b128 v[232:235], v197 offset:5120
	ds_read_b128 v[236:239], v197 offset:6144
	ds_read_b128 v[240:243], v197 offset:7168
	global_load_lds_dwordx4 v[160:161], off
	v_lshl_add_u64 v[160:161], v[134:135], 0, s[10:11]
	s_add_i32 m0, s67, 0xe000
	s_nop 0
	global_load_lds_dwordx4 v[160:161], off
	s_waitcnt vmcnt(8)
	s_cmp_lg_u64 s[42:43], 0
	s_cbranch_scc1 .Llgk_1111_0
	s_waitcnt lgkmcnt(0)
.Llgk_1111_0:
	s_barrier
	s_setprio 1
	s_waitcnt lgkmcnt(0)
	v_mfma_f32_16x16x32_bf16 v[16:19], v[136:139], v[212:215], v[16:19]
	v_mfma_f32_16x16x32_bf16 v[12:15], v[144:147], v[212:215], v[12:15]
	v_mfma_f32_16x16x32_bf16 v[56:59], v[136:139], v[220:223], v[56:59]
	v_mfma_f32_16x16x32_bf16 v[52:55], v[144:147], v[220:223], v[52:55]
	v_mfma_f32_16x16x32_bf16 v[88:91], v[136:139], v[228:231], v[88:91]
	v_mfma_f32_16x16x32_bf16 v[76:79], v[144:147], v[228:231], v[76:79]
	v_mfma_f32_16x16x32_bf16 v[112:115], v[136:139], v[236:239], v[112:115]
	v_mfma_f32_16x16x32_bf16 v[108:111], v[144:147], v[236:239], v[108:111]
	v_mfma_f32_16x16x32_bf16 v[16:19], v[140:143], v[216:219], v[16:19]
	v_mfma_f32_16x16x32_bf16 v[12:15], v[172:175], v[216:219], v[12:15]
	v_mfma_f32_16x16x32_bf16 v[56:59], v[140:143], v[224:227], v[56:59]
	v_mfma_f32_16x16x32_bf16 v[52:55], v[172:175], v[224:227], v[52:55]
	v_mfma_f32_16x16x32_bf16 v[88:91], v[140:143], v[232:235], v[88:91]
	v_mfma_f32_16x16x32_bf16 v[76:79], v[172:175], v[232:235], v[76:79]
	v_mfma_f32_16x16x32_bf16 v[112:115], v[140:143], v[240:243], v[112:115]
	v_mfma_f32_16x16x32_bf16 v[108:111], v[172:175], v[240:243], v[108:111]
	s_setprio 0
	s_setprio 1
	v_mfma_f32_16x16x32_bf16 v[8:11], v[176:179], v[212:215], v[8:11]
	v_mfma_f32_16x16x32_bf16 v[4:7], v[184:187], v[212:215], v[4:7]
	v_mfma_f32_16x16x32_bf16 v[40:43], v[176:179], v[220:223], v[40:43]
	v_mfma_f32_16x16x32_bf16 v[36:39], v[184:187], v[220:223], v[36:39]
	v_mfma_f32_16x16x32_bf16 v[64:67], v[176:179], v[228:231], v[64:67]
	v_mfma_f32_16x16x32_bf16 v[60:63], v[184:187], v[228:231], v[60:63]
	v_mfma_f32_16x16x32_bf16 v[96:99], v[176:179], v[236:239], v[96:99]
	v_mfma_f32_16x16x32_bf16 v[92:95], v[184:187], v[236:239], v[92:95]
	v_mfma_f32_16x16x32_bf16 v[8:11], v[180:183], v[216:219], v[8:11]
	v_mfma_f32_16x16x32_bf16 v[4:7], v[208:211], v[216:219], v[4:7]
	v_mfma_f32_16x16x32_bf16 v[40:43], v[180:183], v[224:227], v[40:43]
	v_mfma_f32_16x16x32_bf16 v[36:39], v[208:211], v[224:227], v[36:39]
	s_setprio 2
	s_barrier
	v_mfma_f32_16x16x32_bf16 v[64:67], v[180:183], v[232:235], v[64:67]
	v_mfma_f32_16x16x32_bf16 v[60:63], v[208:211], v[232:235], v[60:63]
	v_mfma_f32_16x16x32_bf16 v[96:99], v[180:183], v[240:243], v[96:99]
	v_mfma_f32_16x16x32_bf16 v[92:95], v[208:211], v[240:243], v[92:95]
	s_setprio 0
	s_add_i32 s10, s25, s66
	v_lshl_add_u64 v[160:161], s[62:63], 0, v[2:3]
	s_mov_b32 m0, s10
	ds_read_b128 v[212:215], v197 offset:16384
	ds_read_b128 v[216:219], v197 offset:17408
	ds_read_b128 v[220:223], v197 offset:18432
	ds_read_b128 v[224:227], v197 offset:19456
	ds_read_b128 v[228:231], v197 offset:20480
	ds_read_b128 v[232:235], v197 offset:21504
	ds_read_b128 v[236:239], v197 offset:22528
	ds_read_b128 v[240:243], v197 offset:23552
	global_load_lds_dwordx4 v[160:161], off
	s_add_i32 m0, s10, 0x2000
	s_add_u32 s10, s62, 0x160000
	v_lshl_add_u64 v[162:163], s[62:63], 0, v[150:151]
	s_addc_u32 s11, s63, 0
	s_add_i32 s19, s19, s66
	global_load_lds_dwordx4 v[162:163], off
	v_lshl_add_u64 v[244:245], s[10:11], 0, v[2:3]
	s_mov_b32 m0, s19
	v_lshl_add_u64 v[246:247], s[64:65], 0, v[148:149]
	global_load_lds_dwordx4 v[244:245], off
	v_lshl_add_u64 v[244:245], s[10:11], 0, v[150:151]
	s_add_i32 m0, s19, 0x2000
	s_nop 0
	global_load_lds_dwordx4 v[244:245], off
	v_lshl_add_u64 v[244:245], s[64:65], 0, v[0:1]
	s_mov_b32 m0, s67
	s_nop 0
	global_load_lds_dwordx4 v[244:245], off
	s_mov_b32 m0, s75
	s_nop 0
	global_load_lds_dwordx4 v[246:247], off
	s_waitcnt vmcnt(8)
	s_cmp_lg_u64 s[42:43], 0
	s_cbranch_scc1 .Llgk_1111_1
	s_waitcnt lgkmcnt(0)
; #define PG8_STAGE(bufoff, gbase, voff) do { _Pragma("unroll") for (int _i = 0; _i < 2; ++_i) \
;         __builtin_amdgcn_global_load_lds((const unsigned*)((const char*)(gbase) + (voff)[_i]), (LAS unsigned*)(lds + (bufoff) + ldsw + _i * 8192), 16, 0, 0); } while (0)
; #define PG8_LDA(dst, b, h) do { _Pragma("unroll") for (int m = 0; m < 4; ++m) _Pragma("unroll") for (int k = 0; k < 2; ++k) dst[m][k] = *(const LAS bf16x8*)(lds + PG8_SA(b, h) + aoff + m * 2048 + k * 1024); } while (0)
; #define PG8_LDB(dst, b, h) do { _Pragma("unroll") for (int n = 0; n < 2; ++n) _Pragma("unroll") for (int k = 0; k < 2; ++k) dst[n][k] = *(const LAS bf16x8*)(lds + PG8_SB(b, h) + boff + n * 2048 + k * 1024); } while (0)
; #define PG8_MMA(ai, bj, At, Bt) do { __builtin_amdgcn_s_setprio(1); _Pragma("unroll") for (int m = 0; m < 4; ++m) _Pragma("unroll") for (int n = 0; n < 2; ++n) _Pragma("unroll") for (int k = 0; k < 2; ++k) \
;         acc[ai][bj][m][n] = __builtin_amdgcn_mfma_f32_16x16x32_bf16(Bt[n][k], At[m][k], acc[ai][bj][m][n], 0, 0, 0); __builtin_amdgcn_s_setprio(0); } while (0)
; #define PG8_WAIT_V(n) asm volatile("s_waitcnt vmcnt(" #n ")" ::: "memory")
; #define PG8_WAIT_L(n) asm volatile("s_waitcnt lgkmcnt(" #n ")" ::: "memory")
; #define PG8_BAR __builtin_amdgcn_s_barrier()
; #define PG8_SCHED __builtin_amdgcn_sched_barrier(0)
; template <class Epi, class Sched, bool ALIGN_EPI = true>
; __device__ __forceinline__ void gemm_phase(LAS unsigned char* lds, const Gemm g, const Sched& S, const Epi& E) {
;     ...
;             PG8_WAIT_V(8); PG8_WAIT_L(0); PG8_BAR; PG8_MMA(1, 0, At, B0); PG8_MMA(1, 1, At, B1); PG8_BAR; PG8_SCHED;
;             PG8_LDB(B0, 1, 0); PG8_LDB(B1, 1, 1); PG8_SCHED; PG8_LDA(At, 1, 0); PG8_STAGE(PG8_SA(0, 1), a2 + hA, voffA);
;             PG8_WAIT_V(8); PG8_WAIT_L(0); PG8_BAR; PG8_MMA(0, 0, At, B0); PG8_MMA(0, 1, At, B1); PG8_BAR; PG8_SCHED;
.Llgk_1111_1:
	s_barrier
	s_setprio 1
	s_waitcnt lgkmcnt(0)
	v_mfma_f32_16x16x32_bf16 v[128:131], v[136:139], v[212:215], v[128:131]
	v_mfma_f32_16x16x32_bf16 v[124:127], v[144:147], v[212:215], v[124:127]
	v_mfma_f32_16x16x32_bf16 v[104:107], v[136:139], v[220:223], v[104:107]
	v_mfma_f32_16x16x32_bf16 v[100:103], v[144:147], v[220:223], v[100:103]
	v_mfma_f32_16x16x32_bf16 v[72:75], v[136:139], v[228:231], v[72:75]
	v_mfma_f32_16x16x32_bf16 v[68:71], v[144:147], v[228:231], v[68:71]
	v_mfma_f32_16x16x32_bf16 v[32:35], v[136:139], v[236:239], v[32:35]
	v_mfma_f32_16x16x32_bf16 v[28:31], v[144:147], v[236:239], v[28:31]
	v_mfma_f32_16x16x32_bf16 v[128:131], v[140:143], v[216:219], v[128:131]
	v_mfma_f32_16x16x32_bf16 v[124:127], v[172:175], v[216:219], v[124:127]
	v_mfma_f32_16x16x32_bf16 v[104:107], v[140:143], v[224:227], v[104:107]
	v_mfma_f32_16x16x32_bf16 v[100:103], v[172:175], v[224:227], v[100:103]
	v_mfma_f32_16x16x32_bf16 v[72:75], v[140:143], v[232:235], v[72:75]
	v_mfma_f32_16x16x32_bf16 v[68:71], v[172:175], v[232:235], v[68:71]
	v_mfma_f32_16x16x32_bf16 v[32:35], v[140:143], v[240:243], v[32:35]
	v_mfma_f32_16x16x32_bf16 v[28:31], v[172:175], v[240:243], v[28:31]
	s_setprio 0
	s_setprio 1
	v_mfma_f32_16x16x32_bf16 v[120:123], v[176:179], v[212:215], v[120:123]
	v_mfma_f32_16x16x32_bf16 v[116:119], v[184:187], v[212:215], v[116:119]
	v_mfma_f32_16x16x32_bf16 v[84:87], v[176:179], v[220:223], v[84:87]
	v_mfma_f32_16x16x32_bf16 v[80:83], v[184:187], v[220:223], v[80:83]
	v_mfma_f32_16x16x32_bf16 v[48:51], v[176:179], v[228:231], v[48:51]
	v_mfma_f32_16x16x32_bf16 v[44:47], v[184:187], v[228:231], v[44:47]
	v_mfma_f32_16x16x32_bf16 v[24:27], v[176:179], v[236:239], v[24:27]
	v_mfma_f32_16x16x32_bf16 v[20:23], v[184:187], v[236:239], v[20:23]
	v_mfma_f32_16x16x32_bf16 v[120:123], v[180:183], v[216:219], v[120:123]
	v_mfma_f32_16x16x32_bf16 v[116:119], v[208:211], v[216:219], v[116:119]
	v_mfma_f32_16x16x32_bf16 v[84:87], v[180:183], v[224:227], v[84:87]
	v_mfma_f32_16x16x32_bf16 v[80:83], v[208:211], v[224:227], v[80:83]
	s_setprio 2
	s_barrier
	v_mfma_f32_16x16x32_bf16 v[48:51], v[180:183], v[232:235], v[48:51]
	v_mfma_f32_16x16x32_bf16 v[44:47], v[208:211], v[232:235], v[44:47]
	v_mfma_f32_16x16x32_bf16 v[24:27], v[180:183], v[240:243], v[24:27]
	v_mfma_f32_16x16x32_bf16 v[20:23], v[208:211], v[240:243], v[20:23]
	s_setprio 0
	s_add_i32 s19, 0, 0x18000
	s_add_i32 s24, 0, 0x1c000
	v_add_u32_e32 v172, s19, v188
	v_add_u32_e32 v207, s24, v188
	ds_read_b128 v[136:139], v172
	ds_read_b128 v[140:143], v172 offset:1024
	ds_read_b128 v[144:147], v172 offset:2048
	ds_read_b128 v[172:175], v172 offset:3072
	ds_read_b128 v[176:179], v207
	ds_read_b128 v[180:183], v207 offset:1024
	ds_read_b128 v[184:187], v207 offset:2048
	ds_read_b128 v[208:211], v207 offset:3072
	s_add_u32 s10, s64, 0x160000
	s_addc_u32 s11, s65, 0
	s_mov_b32 m0, s76
	v_lshl_add_u64 v[248:249], s[10:11], 0, v[0:1]
	ds_read_b128 v[212:215], v197 offset:32768
	ds_read_b128 v[216:219], v197 offset:33792
	ds_read_b128 v[220:223], v197 offset:34816
	ds_read_b128 v[224:227], v197 offset:35840
	ds_read_b128 v[228:231], v197 offset:36864
	ds_read_b128 v[232:235], v197 offset:37888
	ds_read_b128 v[236:239], v197 offset:38912
	ds_read_b128 v[240:243], v197 offset:39936
	global_load_lds_dwordx4 v[248:249], off
	v_lshl_add_u64 v[248:249], s[10:11], 0, v[148:149]
	s_mov_b32 m0, s77
	s_nop 0
	global_load_lds_dwordx4 v[248:249], off
	s_waitcnt vmcnt(8)
	s_cmp_lg_u64 s[42:43], 0
	s_cbranch_scc1 .Llgk_1111_2
	s_waitcnt lgkmcnt(0)
; #define PG8_STAGE(bufoff, gbase, voff) do { _Pragma("unroll") for (int _i = 0; _i < 2; ++_i) \
;         __builtin_amdgcn_global_load_lds((const unsigned*)((const char*)(gbase) + (voff)[_i]), (LAS unsigned*)(lds + (bufoff) + ldsw + _i * 8192), 16, 0, 0); } while (0)
; #define PG8_LDA(dst, b, h) do { _Pragma("unroll") for (int m = 0; m < 4; ++m) _Pragma("unroll") for (int k = 0; k < 2; ++k) dst[m][k] = *(const LAS bf16x8*)(lds + PG8_SA(b, h) + aoff + m * 2048 + k * 1024); } while (0)
; #define PG8_MMA(ai, bj, At, Bt) do { __builtin_amdgcn_s_setprio(1); _Pragma("unroll") for (int m = 0; m < 4; ++m) _Pragma("unroll") for (int n = 0; n < 2; ++n) _Pragma("unroll") for (int k = 0; k < 2; ++k) \
;         acc[ai][bj][m][n] = __builtin_amdgcn_mfma_f32_16x16x32_bf16(Bt[n][k], At[m][k], acc[ai][bj][m][n], 0, 0, 0); __builtin_amdgcn_s_setprio(0); } while (0)
; #define PG8_WAIT_V(n) asm volatile("s_waitcnt vmcnt(" #n ")" ::: "memory")
; #define PG8_WAIT_L(n) asm volatile("s_waitcnt lgkmcnt(" #n ")" ::: "memory")
; #define PG8_BAR __builtin_amdgcn_s_barrier()
; #define PG8_SCHED __builtin_amdgcn_sched_barrier(0)
; template <class Epi, class Sched, bool ALIGN_EPI = true>
; __device__ __forceinline__ void gemm_phase(LAS unsigned char* lds, const Gemm g, const Sched& S, const Epi& E) {
;     ...
;             PG8_WAIT_V(8); PG8_WAIT_L(0); PG8_BAR; PG8_MMA(0, 0, At, B0); PG8_MMA(0, 1, At, B1); PG8_BAR; PG8_SCHED;
;             PG8_LDA(At, 1, 1); PG8_STAGE(PG8_SB(1, 0), b3, voffB); PG8_STAGE(PG8_SB(1, 1), b3 + hB, voffB); PG8_STAGE(PG8_SA(1, 0), a3, voffA);
;             PG8_WAIT_V(8); PG8_WAIT_L(0); PG8_BAR; PG8_MMA(1, 0, At, B0); PG8_MMA(1, 1, At, B1); PG8_BAR; PG8_SCHED;
;         }
;         if constexpr (ALIGN_EPI) { if (wr == 0) PG8_BAR; }
.Llgk_1111_2:
	s_barrier
	s_setprio 1
	s_waitcnt lgkmcnt(0)
	v_mfma_f32_16x16x32_bf16 v[16:19], v[136:139], v[212:215], v[16:19]
	v_mfma_f32_16x16x32_bf16 v[12:15], v[144:147], v[212:215], v[12:15]
	v_mfma_f32_16x16x32_bf16 v[56:59], v[136:139], v[220:223], v[56:59]
	v_mfma_f32_16x16x32_bf16 v[52:55], v[144:147], v[220:223], v[52:55]
	v_mfma_f32_16x16x32_bf16 v[88:91], v[136:139], v[228:231], v[88:91]
	v_mfma_f32_16x16x32_bf16 v[76:79], v[144:147], v[228:231], v[76:79]
	v_mfma_f32_16x16x32_bf16 v[112:115], v[136:139], v[236:239], v[112:115]
	v_mfma_f32_16x16x32_bf16 v[108:111], v[144:147], v[236:239], v[108:111]
	v_mfma_f32_16x16x32_bf16 v[16:19], v[140:143], v[216:219], v[16:19]
	v_mfma_f32_16x16x32_bf16 v[12:15], v[172:175], v[216:219], v[12:15]
	v_mfma_f32_16x16x32_bf16 v[56:59], v[140:143], v[224:227], v[56:59]
	v_mfma_f32_16x16x32_bf16 v[52:55], v[172:175], v[224:227], v[52:55]
	v_mfma_f32_16x16x32_bf16 v[88:91], v[140:143], v[232:235], v[88:91]
	v_mfma_f32_16x16x32_bf16 v[76:79], v[172:175], v[232:235], v[76:79]
	v_mfma_f32_16x16x32_bf16 v[112:115], v[140:143], v[240:243], v[112:115]
	v_mfma_f32_16x16x32_bf16 v[108:111], v[172:175], v[240:243], v[108:111]
	s_setprio 0
	s_setprio 1
	v_mfma_f32_16x16x32_bf16 v[8:11], v[176:179], v[212:215], v[8:11]
	v_mfma_f32_16x16x32_bf16 v[4:7], v[184:187], v[212:215], v[4:7]
	v_mfma_f32_16x16x32_bf16 v[40:43], v[176:179], v[220:223], v[40:43]
	v_mfma_f32_16x16x32_bf16 v[36:39], v[184:187], v[220:223], v[36:39]
	v_mfma_f32_16x16x32_bf16 v[64:67], v[176:179], v[228:231], v[64:67]
	v_mfma_f32_16x16x32_bf16 v[60:63], v[184:187], v[228:231], v[60:63]
	v_mfma_f32_16x16x32_bf16 v[96:99], v[176:179], v[236:239], v[96:99]
	v_mfma_f32_16x16x32_bf16 v[92:95], v[184:187], v[236:239], v[92:95]
	v_mfma_f32_16x16x32_bf16 v[8:11], v[180:183], v[216:219], v[8:11]
	v_mfma_f32_16x16x32_bf16 v[4:7], v[208:211], v[216:219], v[4:7]
	v_mfma_f32_16x16x32_bf16 v[40:43], v[180:183], v[224:227], v[40:43]
	v_mfma_f32_16x16x32_bf16 v[36:39], v[208:211], v[224:227], v[36:39]
	s_setprio 2
	s_barrier
	v_mfma_f32_16x16x32_bf16 v[64:67], v[180:183], v[232:235], v[64:67]
	v_mfma_f32_16x16x32_bf16 v[60:63], v[208:211], v[232:235], v[60:63]
	v_mfma_f32_16x16x32_bf16 v[96:99], v[180:183], v[240:243], v[96:99]
	v_mfma_f32_16x16x32_bf16 v[92:95], v[208:211], v[240:243], v[92:95]
	s_setprio 0
	s_add_i32 s10, s19, s66
	v_lshl_add_u64 v[160:161], v[160:161], 0, s[86:87]
	s_mov_b32 m0, s10
	ds_read_b128 v[212:215], v197 offset:49152
	ds_read_b128 v[216:219], v197 offset:50176
	ds_read_b128 v[220:223], v197 offset:51200
	ds_read_b128 v[224:227], v197 offset:52224
	ds_read_b128 v[228:231], v197 offset:53248
	ds_read_b128 v[232:235], v197 offset:54272
	ds_read_b128 v[236:239], v197 offset:55296
	ds_read_b128 v[240:243], v197 offset:56320
	global_load_lds_dwordx4 v[160:161], off
	s_add_i32 m0, s10, 0x2000
	s_add_u32 s10, s62, 0x160080
	v_lshl_add_u64 v[160:161], v[162:163], 0, s[86:87]
	s_addc_u32 s11, s63, 0
	s_add_i32 s19, s24, s66
	global_load_lds_dwordx4 v[160:161], off
	v_lshl_add_u64 v[160:161], s[10:11], 0, v[2:3]
	s_mov_b32 m0, s19
	s_nop 0
	global_load_lds_dwordx4 v[160:161], off
	v_lshl_add_u64 v[160:161], s[10:11], 0, v[150:151]
	s_add_i32 m0, s19, 0x2000
	s_nop 0
	global_load_lds_dwordx4 v[160:161], off
	v_lshl_add_u64 v[160:161], v[244:245], 0, s[86:87]
	s_mov_b32 m0, s80
	s_nop 0
	global_load_lds_dwordx4 v[160:161], off
	v_lshl_add_u64 v[160:161], v[246:247], 0, s[86:87]
	s_mov_b32 m0, s81
	s_nop 0
	global_load_lds_dwordx4 v[160:161], off
	s_waitcnt vmcnt(8)
	s_cmp_lg_u64 s[42:43], 0
	s_cbranch_scc1 .Llgk_1111_3
	s_waitcnt lgkmcnt(0)
.Llgk_1111_3:
	s_barrier
	s_setprio 1
	s_waitcnt lgkmcnt(0)
	v_mfma_f32_16x16x32_bf16 v[128:131], v[136:139], v[212:215], v[128:131]
	v_mfma_f32_16x16x32_bf16 v[124:127], v[144:147], v[212:215], v[124:127]
	v_mfma_f32_16x16x32_bf16 v[104:107], v[136:139], v[220:223], v[104:107]
	v_mfma_f32_16x16x32_bf16 v[100:103], v[144:147], v[220:223], v[100:103]
	v_mfma_f32_16x16x32_bf16 v[72:75], v[136:139], v[228:231], v[72:75]
	v_mfma_f32_16x16x32_bf16 v[68:71], v[144:147], v[228:231], v[68:71]
	v_mfma_f32_16x16x32_bf16 v[32:35], v[136:139], v[236:239], v[32:35]
	v_mfma_f32_16x16x32_bf16 v[28:31], v[144:147], v[236:239], v[28:31]
	v_mfma_f32_16x16x32_bf16 v[128:131], v[140:143], v[216:219], v[128:131]
	v_mfma_f32_16x16x32_bf16 v[124:127], v[172:175], v[216:219], v[124:127]
	v_mfma_f32_16x16x32_bf16 v[104:107], v[140:143], v[224:227], v[104:107]
	v_mfma_f32_16x16x32_bf16 v[100:103], v[172:175], v[224:227], v[100:103]
	v_mfma_f32_16x16x32_bf16 v[72:75], v[140:143], v[232:235], v[72:75]
	v_mfma_f32_16x16x32_bf16 v[68:71], v[172:175], v[232:235], v[68:71]
	v_mfma_f32_16x16x32_bf16 v[32:35], v[140:143], v[240:243], v[32:35]
	v_mfma_f32_16x16x32_bf16 v[28:31], v[172:175], v[240:243], v[28:31]
	s_setprio 0
	s_setprio 1
	v_mfma_f32_16x16x32_bf16 v[120:123], v[176:179], v[212:215], v[120:123]
	v_mfma_f32_16x16x32_bf16 v[116:119], v[184:187], v[212:215], v[116:119]
	v_mfma_f32_16x16x32_bf16 v[84:87], v[176:179], v[220:223], v[84:87]
	v_mfma_f32_16x16x32_bf16 v[80:83], v[184:187], v[220:223], v[80:83]
	v_mfma_f32_16x16x32_bf16 v[48:51], v[176:179], v[228:231], v[48:51]
	v_mfma_f32_16x16x32_bf16 v[44:47], v[184:187], v[228:231], v[44:47]
	v_mfma_f32_16x16x32_bf16 v[24:27], v[176:179], v[236:239], v[24:27]
	v_mfma_f32_16x16x32_bf16 v[20:23], v[184:187], v[236:239], v[20:23]
	v_mfma_f32_16x16x32_bf16 v[120:123], v[180:183], v[216:219], v[120:123]
	v_mfma_f32_16x16x32_bf16 v[116:119], v[208:211], v[216:219], v[116:119]
	v_mfma_f32_16x16x32_bf16 v[84:87], v[180:183], v[224:227], v[84:87]
	v_mfma_f32_16x16x32_bf16 v[80:83], v[208:211], v[224:227], v[80:83]
	s_setprio 2
	s_barrier
	v_mfma_f32_16x16x32_bf16 v[48:51], v[180:183], v[232:235], v[48:51]
	v_mfma_f32_16x16x32_bf16 v[44:47], v[208:211], v[232:235], v[44:47]
	v_mfma_f32_16x16x32_bf16 v[24:27], v[180:183], v[240:243], v[24:27]
	v_mfma_f32_16x16x32_bf16 v[20:23], v[208:211], v[240:243], v[20:23]
	s_setprio 0
	s_add_i32 s18, s18, 2
	s_cmpk_gt_u32 s18, 0x55
	s_mov_b64 s[10:11], vcc
	s_cbranch_scc0 .LBB0_1111
	s_and_b64 vcc, exec, s[42:43]
	s_cbranch_vccz .LBB0_1114
	s_barrier
